# K-loop back edge rotated: the six loop-control SALU instructions of every GEMM K-loop issue under the tail of the last MFMA block, before s_setprio 0 / s_barrier, instead of after the barrier
# baseline (speedup 1.0000x reference)
; #define PG8_STAGE(bufoff, gbase, voff) do { _Pragma("unroll") for (int _i = 0; _i < 2; ++_i) \
;         __builtin_amdgcn_global_load_lds((const unsigned*)((const char*)(gbase) + (voff)[_i]), (PG8_LAS unsigned*)(lds + (bufoff) + ldsw + _i * 8192), 16, 0, 0); } while (0)
; #define PG8_LDA(dst, b, h) do { _Pragma("unroll") for (int m = 0; m < 4; ++m) _Pragma("unroll") for (int k = 0; k < 2; ++k) dst[m][k] = *(const PG8_LAS bf16x8*)(lds + PG8_SA(b, h) + aoff + m * 2048 + k * 1024); } while (0)
; #define PG8_LDB(dst, b, h) do { _Pragma("unroll") for (int n = 0; n < 2; ++n) _Pragma("unroll") for (int k = 0; k < 2; ++k) dst[n][k] = *(const PG8_LAS bf16x8*)(lds + PG8_SB(b, h) + boff + n * 2048 + k * 1024); } while (0)
; #define PG8_MMA(ai, bj, At, Bt) do { __builtin_amdgcn_s_setprio(1); _Pragma("unroll") for (int m = 0; m < 4; ++m) _Pragma("unroll") for (int n = 0; n < 2; ++n) _Pragma("unroll") for (int k = 0; k < 2; ++k) \
;         acc[ai][bj][m][n] = __builtin_amdgcn_mfma_f32_16x16x32_bf16(Bt[n][k], At[m][k], acc[ai][bj][m][n], 0, 0, 0); __builtin_amdgcn_s_setprio(0); } while (0)
; #define PG8_WAIT_V(n) asm volatile("s_waitcnt vmcnt(" #n ")" ::: "memory")
; #define PG8_WAIT_L(n) asm volatile("s_waitcnt lgkmcnt(" #n ")" ::: "memory")
; #define PG8_BAR __builtin_amdgcn_s_barrier()
; #define PG8_SCHED __builtin_amdgcn_sched_barrier(0)
; template <class Epi, class Sched, bool ALIGN_EPI = false, bool SP2 = false>
; __device__ __forceinline__ void gemm_phase(PG8_LAS unsigned char* lds, const Gemm g, const Sched& S, const Epi& E) {
;     ...
;             PG8_LDB(B0, 0, 0); PG8_LDB(B1, 0, 1); PG8_SCHED; PG8_LDA(At, 0, 0); PG8_STAGE(PG8_SA(1, 1), a1 + hstepA, voffA);
;             PG8_WAIT_V(8); PG8_WAIT_L(0); PG8_BAR; PG8_MMA(0, 0, At, B0); PG8_MMA(0, 1, At, B1); PG8_BAR; PG8_SCHED;
;             PG8_LDA(At, 0, 1); PG8_STAGE(PG8_SB(0, 0), b2, voffB); PG8_STAGE(PG8_SB(0, 1), b2 + hstepB, voffB); PG8_STAGE(PG8_SA(0, 0), a2, voffA);
;             PG8_WAIT_V(8); PG8_WAIT_L(0); PG8_BAR; PG8_MMA(1, 0, At, B0); PG8_MMA(1, 1, At, B1); PG8_BAR; PG8_SCHED;
.LBB0_122:
	ds_read_b128 v[146:149], v161
	ds_read_b128 v[150:153], v161 offset:1024
	ds_read_b128 v[166:169], v161 offset:2048
	ds_read_b128 v[170:173], v161 offset:3072
	ds_read_b128 v[174:177], v162
	ds_read_b128 v[178:181], v162 offset:1024
	ds_read_b128 v[182:185], v162 offset:2048
	ds_read_b128 v[186:189], v162 offset:3072
	s_add_u32 s26, s6, 0xfff00080
	s_addc_u32 s27, s7, -1
	s_cmp_eq_u32 s31, 28
	s_cselect_b32 s29, s3, s27
	s_cselect_b32 s28, s5, s26
	s_cselect_b32 s27, s10, s30
	s_cselect_b32 s26, s19, s21
	v_lshl_add_u64 v[154:155], s[6:7], 0, v[138:139]
	s_add_i32 m0, s39, 0xc000
	ds_read_b128 v[190:193], v163
	ds_read_b128 v[194:197], v163 offset:1024
	ds_read_b128 v[198:201], v163 offset:2048
	ds_read_b128 v[202:205], v163 offset:3072
	ds_read_b128 v[206:209], v163 offset:4096
	ds_read_b128 v[210:213], v163 offset:5120
	ds_read_b128 v[214:217], v163 offset:6144
	ds_read_b128 v[218:221], v163 offset:7168
	global_load_lds_dwordx4 v[154:155], off
	v_lshl_add_u64 v[154:155], s[6:7], 0, v[140:141]
	s_add_i32 m0, s39, 0xe000
	s_nop 0
	global_load_lds_dwordx4 v[154:155], off
	s_waitcnt vmcnt(8)
	s_waitcnt lgkmcnt(0)
	s_barrier
	s_setprio 1
	s_waitcnt lgkmcnt(0)
	v_mfma_f32_16x16x32_bf16 v[124:127], v[146:149], v[190:193], v[124:127]
	v_mfma_f32_16x16x32_bf16 v[120:123], v[166:169], v[190:193], v[120:123]
	v_mfma_f32_16x16x32_bf16 v[108:111], v[146:149], v[198:201], v[108:111]
	v_mfma_f32_16x16x32_bf16 v[104:107], v[166:169], v[198:201], v[104:107]
	v_mfma_f32_16x16x32_bf16 v[92:95], v[146:149], v[206:209], v[92:95]
	v_mfma_f32_16x16x32_bf16 v[88:91], v[166:169], v[206:209], v[88:91]
	v_mfma_f32_16x16x32_bf16 v[76:79], v[146:149], v[214:217], v[76:79]
	v_mfma_f32_16x16x32_bf16 v[72:75], v[166:169], v[214:217], v[72:75]
	v_mfma_f32_16x16x32_bf16 v[124:127], v[150:153], v[194:197], v[124:127]
	v_mfma_f32_16x16x32_bf16 v[120:123], v[170:173], v[194:197], v[120:123]
	v_mfma_f32_16x16x32_bf16 v[108:111], v[150:153], v[202:205], v[108:111]
	v_mfma_f32_16x16x32_bf16 v[104:107], v[170:173], v[202:205], v[104:107]
	v_mfma_f32_16x16x32_bf16 v[92:95], v[150:153], v[210:213], v[92:95]
	v_mfma_f32_16x16x32_bf16 v[88:91], v[170:173], v[210:213], v[88:91]
	v_mfma_f32_16x16x32_bf16 v[76:79], v[150:153], v[218:221], v[76:79]
	v_mfma_f32_16x16x32_bf16 v[72:75], v[170:173], v[218:221], v[72:75]
	v_mfma_f32_16x16x32_bf16 v[116:119], v[174:177], v[190:193], v[116:119]
	v_mfma_f32_16x16x32_bf16 v[112:115], v[182:185], v[190:193], v[112:115]
	v_mfma_f32_16x16x32_bf16 v[100:103], v[174:177], v[198:201], v[100:103]
	v_mfma_f32_16x16x32_bf16 v[96:99], v[182:185], v[198:201], v[96:99]
	v_mfma_f32_16x16x32_bf16 v[84:87], v[174:177], v[206:209], v[84:87]
	v_mfma_f32_16x16x32_bf16 v[80:83], v[182:185], v[206:209], v[80:83]
	v_mfma_f32_16x16x32_bf16 v[68:71], v[174:177], v[214:217], v[68:71]
	v_mfma_f32_16x16x32_bf16 v[64:67], v[182:185], v[214:217], v[64:67]
	v_mfma_f32_16x16x32_bf16 v[116:119], v[178:181], v[194:197], v[116:119]
	v_mfma_f32_16x16x32_bf16 v[112:115], v[186:189], v[194:197], v[112:115]
	v_mfma_f32_16x16x32_bf16 v[100:103], v[178:181], v[202:205], v[100:103]
	v_mfma_f32_16x16x32_bf16 v[96:99], v[186:189], v[202:205], v[96:99]
	v_mfma_f32_16x16x32_bf16 v[84:87], v[178:181], v[210:213], v[84:87]
	v_mfma_f32_16x16x32_bf16 v[80:83], v[186:189], v[210:213], v[80:83]
	v_mfma_f32_16x16x32_bf16 v[68:71], v[178:181], v[218:221], v[68:71]
	v_mfma_f32_16x16x32_bf16 v[64:67], v[186:189], v[218:221], v[64:67]
	s_setprio 0
	s_barrier
	s_add_i32 s34, s54, s38
	v_lshl_add_u64 v[154:155], s[26:27], 0, v[130:131]
	s_mov_b32 m0, s34
	ds_read_b128 v[190:193], v163 offset:16384
	ds_read_b128 v[194:197], v163 offset:17408
	ds_read_b128 v[198:201], v163 offset:18432
	ds_read_b128 v[202:205], v163 offset:19456
	ds_read_b128 v[206:209], v163 offset:20480
	ds_read_b128 v[210:213], v163 offset:21504
	ds_read_b128 v[214:217], v163 offset:22528
	ds_read_b128 v[218:221], v163 offset:23552
	global_load_lds_dwordx4 v[154:155], off
	s_add_i32 m0, s34, 0x2000
	s_add_u32 s34, s26, 0x80000
	v_lshl_add_u64 v[222:223], s[26:27], 0, v[134:135]
	s_addc_u32 s35, s27, 0
	s_add_i32 s68, s55, s38
	global_load_lds_dwordx4 v[222:223], off
	v_lshl_add_u64 v[224:225], s[34:35], 0, v[130:131]
	s_mov_b32 m0, s68
	v_lshl_add_u64 v[226:227], s[28:29], 0, v[132:133]
	global_load_lds_dwordx4 v[224:225], off
	v_lshl_add_u64 v[224:225], s[34:35], 0, v[134:135]
	s_add_i32 m0, s68, 0x2000
	s_nop 0
	global_load_lds_dwordx4 v[224:225], off
	v_lshl_add_u64 v[224:225], s[28:29], 0, v[128:129]
	s_mov_b32 m0, s39
	s_nop 0
	global_load_lds_dwordx4 v[224:225], off
	s_mov_b32 m0, s40
	s_nop 0
	global_load_lds_dwordx4 v[226:227], off
	s_waitcnt vmcnt(8)
	s_waitcnt lgkmcnt(0)
	s_barrier
; #define PG8_STAGE(bufoff, gbase, voff) do { _Pragma("unroll") for (int _i = 0; _i < 2; ++_i) \
;         __builtin_amdgcn_global_load_lds((const unsigned*)((const char*)(gbase) + (voff)[_i]), (PG8_LAS unsigned*)(lds + (bufoff) + ldsw + _i * 8192), 16, 0, 0); } while (0)
; #define PG8_LDA(dst, b, h) do { _Pragma("unroll") for (int m = 0; m < 4; ++m) _Pragma("unroll") for (int k = 0; k < 2; ++k) dst[m][k] = *(const PG8_LAS bf16x8*)(lds + PG8_SA(b, h) + aoff + m * 2048 + k * 1024); } while (0)
; #define PG8_LDB(dst, b, h) do { _Pragma("unroll") for (int n = 0; n < 2; ++n) _Pragma("unroll") for (int k = 0; k < 2; ++k) dst[n][k] = *(const PG8_LAS bf16x8*)(lds + PG8_SB(b, h) + boff + n * 2048 + k * 1024); } while (0)
; #define PG8_MMA(ai, bj, At, Bt) do { __builtin_amdgcn_s_setprio(1); _Pragma("unroll") for (int m = 0; m < 4; ++m) _Pragma("unroll") for (int n = 0; n < 2; ++n) _Pragma("unroll") for (int k = 0; k < 2; ++k) \
;         acc[ai][bj][m][n] = __builtin_amdgcn_mfma_f32_16x16x32_bf16(Bt[n][k], At[m][k], acc[ai][bj][m][n], 0, 0, 0); __builtin_amdgcn_s_setprio(0); } while (0)
; #define PG8_WAIT_V(n) asm volatile("s_waitcnt vmcnt(" #n ")" ::: "memory")
; #define PG8_WAIT_L(n) asm volatile("s_waitcnt lgkmcnt(" #n ")" ::: "memory")
; #define PG8_BAR __builtin_amdgcn_s_barrier()
; #define PG8_SCHED __builtin_amdgcn_sched_barrier(0)
; template <class Epi, class Sched, bool ALIGN_EPI = false, bool SP2 = false>
; __device__ __forceinline__ void gemm_phase(PG8_LAS unsigned char* lds, const Gemm g, const Sched& S, const Epi& E) {
;     ...
;             PG8_WAIT_V(8); PG8_WAIT_L(0); PG8_BAR; PG8_MMA(1, 0, At, B0); PG8_MMA(1, 1, At, B1); PG8_BAR; PG8_SCHED;
;             PG8_LDB(B0, 1, 0); PG8_LDB(B1, 1, 1); PG8_SCHED; PG8_LDA(At, 1, 0); PG8_STAGE(PG8_SA(0, 1), a2 + hstepA, voffA);
;             PG8_WAIT_V(8); PG8_WAIT_L(0); PG8_BAR; PG8_MMA(0, 0, At, B0); PG8_MMA(0, 1, At, B1); PG8_BAR; PG8_SCHED;
;             PG8_LDA(At, 1, 1); PG8_STAGE(PG8_SB(1, 0), b3, voffB); PG8_STAGE(PG8_SB(1, 1), b3 + hstepB, voffB); PG8_STAGE(PG8_SA(1, 0), a3, voffA);
	s_setprio 1
	s_waitcnt lgkmcnt(0)
	v_mfma_f32_16x16x32_bf16 v[60:63], v[146:149], v[190:193], v[60:63]
	v_mfma_f32_16x16x32_bf16 v[56:59], v[166:169], v[190:193], v[56:59]
	v_mfma_f32_16x16x32_bf16 v[44:47], v[146:149], v[198:201], v[44:47]
	v_mfma_f32_16x16x32_bf16 v[40:43], v[166:169], v[198:201], v[40:43]
	v_mfma_f32_16x16x32_bf16 v[28:31], v[146:149], v[206:209], v[28:31]
	v_mfma_f32_16x16x32_bf16 v[24:27], v[166:169], v[206:209], v[24:27]
	v_mfma_f32_16x16x32_bf16 v[12:15], v[146:149], v[214:217], v[12:15]
	v_mfma_f32_16x16x32_bf16 v[8:11], v[166:169], v[214:217], v[8:11]
	v_mfma_f32_16x16x32_bf16 v[60:63], v[150:153], v[194:197], v[60:63]
	v_mfma_f32_16x16x32_bf16 v[56:59], v[170:173], v[194:197], v[56:59]
	v_mfma_f32_16x16x32_bf16 v[44:47], v[150:153], v[202:205], v[44:47]
	v_mfma_f32_16x16x32_bf16 v[40:43], v[170:173], v[202:205], v[40:43]
	v_mfma_f32_16x16x32_bf16 v[28:31], v[150:153], v[210:213], v[28:31]
	v_mfma_f32_16x16x32_bf16 v[24:27], v[170:173], v[210:213], v[24:27]
	v_mfma_f32_16x16x32_bf16 v[12:15], v[150:153], v[218:221], v[12:15]
	v_mfma_f32_16x16x32_bf16 v[8:11], v[170:173], v[218:221], v[8:11]
	v_mfma_f32_16x16x32_bf16 v[52:55], v[174:177], v[190:193], v[52:55]
	v_mfma_f32_16x16x32_bf16 v[48:51], v[182:185], v[190:193], v[48:51]
	v_mfma_f32_16x16x32_bf16 v[36:39], v[174:177], v[198:201], v[36:39]
	v_mfma_f32_16x16x32_bf16 v[32:35], v[182:185], v[198:201], v[32:35]
	v_mfma_f32_16x16x32_bf16 v[20:23], v[174:177], v[206:209], v[20:23]
	v_mfma_f32_16x16x32_bf16 v[16:19], v[182:185], v[206:209], v[16:19]
	v_mfma_f32_16x16x32_bf16 v[4:7], v[174:177], v[214:217], v[4:7]
	v_mfma_f32_16x16x32_bf16 v[0:3], v[182:185], v[214:217], v[0:3]
	v_mfma_f32_16x16x32_bf16 v[52:55], v[178:181], v[194:197], v[52:55]
	v_mfma_f32_16x16x32_bf16 v[48:51], v[186:189], v[194:197], v[48:51]
	v_mfma_f32_16x16x32_bf16 v[36:39], v[178:181], v[202:205], v[36:39]
	v_mfma_f32_16x16x32_bf16 v[32:35], v[186:189], v[202:205], v[32:35]
	v_mfma_f32_16x16x32_bf16 v[20:23], v[178:181], v[210:213], v[20:23]
	v_mfma_f32_16x16x32_bf16 v[16:19], v[186:189], v[210:213], v[16:19]
	v_mfma_f32_16x16x32_bf16 v[4:7], v[178:181], v[218:221], v[4:7]
	v_mfma_f32_16x16x32_bf16 v[0:3], v[186:189], v[218:221], v[0:3]
	s_setprio 0
	s_barrier
	s_add_i32 s34, 0, 0x18000
	v_add_u32_e32 v136, s34, v159
	s_add_i32 s35, 0, 0x1c000
	ds_read_b128 v[146:149], v136
	ds_read_b128 v[150:153], v136 offset:1024
	ds_read_b128 v[166:169], v136 offset:2048
	ds_read_b128 v[170:173], v136 offset:3072
	v_add_u32_e32 v136, s35, v159
	ds_read_b128 v[174:177], v136
	ds_read_b128 v[178:181], v136 offset:1024
	ds_read_b128 v[182:185], v136 offset:2048
	ds_read_b128 v[186:189], v136 offset:3072
	s_add_u32 s28, s28, 0x100000
	s_addc_u32 s29, s29, 0
	s_mov_b32 m0, s41
	v_lshl_add_u64 v[228:229], s[28:29], 0, v[128:129]
	ds_read_b128 v[190:193], v163 offset:32768
	ds_read_b128 v[194:197], v163 offset:33792
	ds_read_b128 v[198:201], v163 offset:34816
	ds_read_b128 v[202:205], v163 offset:35840
	ds_read_b128 v[206:209], v163 offset:36864
	ds_read_b128 v[210:213], v163 offset:37888
	ds_read_b128 v[214:217], v163 offset:38912
	ds_read_b128 v[218:221], v163 offset:39936
	global_load_lds_dwordx4 v[228:229], off
	v_lshl_add_u64 v[228:229], s[28:29], 0, v[132:133]
	s_mov_b32 m0, s42
	s_nop 0
	global_load_lds_dwordx4 v[228:229], off
	s_waitcnt vmcnt(8)
	s_waitcnt lgkmcnt(0)
	s_barrier
	s_setprio 1
	s_waitcnt lgkmcnt(0)
	v_mfma_f32_16x16x32_bf16 v[124:127], v[146:149], v[190:193], v[124:127]
	v_mfma_f32_16x16x32_bf16 v[120:123], v[166:169], v[190:193], v[120:123]
	v_mfma_f32_16x16x32_bf16 v[108:111], v[146:149], v[198:201], v[108:111]
	v_mfma_f32_16x16x32_bf16 v[104:107], v[166:169], v[198:201], v[104:107]
	v_mfma_f32_16x16x32_bf16 v[92:95], v[146:149], v[206:209], v[92:95]
	v_mfma_f32_16x16x32_bf16 v[88:91], v[166:169], v[206:209], v[88:91]
	v_mfma_f32_16x16x32_bf16 v[76:79], v[146:149], v[214:217], v[76:79]
	v_mfma_f32_16x16x32_bf16 v[72:75], v[166:169], v[214:217], v[72:75]
	v_mfma_f32_16x16x32_bf16 v[124:127], v[150:153], v[194:197], v[124:127]
	v_mfma_f32_16x16x32_bf16 v[120:123], v[170:173], v[194:197], v[120:123]
	v_mfma_f32_16x16x32_bf16 v[108:111], v[150:153], v[202:205], v[108:111]
	v_mfma_f32_16x16x32_bf16 v[104:107], v[170:173], v[202:205], v[104:107]
	v_mfma_f32_16x16x32_bf16 v[92:95], v[150:153], v[210:213], v[92:95]
	v_mfma_f32_16x16x32_bf16 v[88:91], v[170:173], v[210:213], v[88:91]
	v_mfma_f32_16x16x32_bf16 v[76:79], v[150:153], v[218:221], v[76:79]
	v_mfma_f32_16x16x32_bf16 v[72:75], v[170:173], v[218:221], v[72:75]
	v_mfma_f32_16x16x32_bf16 v[116:119], v[174:177], v[190:193], v[116:119]
	v_mfma_f32_16x16x32_bf16 v[112:115], v[182:185], v[190:193], v[112:115]
	v_mfma_f32_16x16x32_bf16 v[100:103], v[174:177], v[198:201], v[100:103]
	v_mfma_f32_16x16x32_bf16 v[96:99], v[182:185], v[198:201], v[96:99]
	v_mfma_f32_16x16x32_bf16 v[84:87], v[174:177], v[206:209], v[84:87]
	v_mfma_f32_16x16x32_bf16 v[80:83], v[182:185], v[206:209], v[80:83]
	v_mfma_f32_16x16x32_bf16 v[68:71], v[174:177], v[214:217], v[68:71]
	v_mfma_f32_16x16x32_bf16 v[64:67], v[182:185], v[214:217], v[64:67]
	v_mfma_f32_16x16x32_bf16 v[116:119], v[178:181], v[194:197], v[116:119]
	v_mfma_f32_16x16x32_bf16 v[112:115], v[186:189], v[194:197], v[112:115]
	v_mfma_f32_16x16x32_bf16 v[100:103], v[178:181], v[202:205], v[100:103]
	v_mfma_f32_16x16x32_bf16 v[96:99], v[186:189], v[202:205], v[96:99]
	v_mfma_f32_16x16x32_bf16 v[84:87], v[178:181], v[210:213], v[84:87]
	v_mfma_f32_16x16x32_bf16 v[80:83], v[186:189], v[210:213], v[80:83]
	v_mfma_f32_16x16x32_bf16 v[68:71], v[178:181], v[218:221], v[68:71]
	v_mfma_f32_16x16x32_bf16 v[64:67], v[186:189], v[218:221], v[64:67]
	s_setprio 0
	s_barrier
; #define PG8_STAGE(bufoff, gbase, voff) do { _Pragma("unroll") for (int _i = 0; _i < 2; ++_i) \
;         __builtin_amdgcn_global_load_lds((const unsigned*)((const char*)(gbase) + (voff)[_i]), (PG8_LAS unsigned*)(lds + (bufoff) + ldsw + _i * 8192), 16, 0, 0); } while (0)
; #define PG8_LDA(dst, b, h) do { _Pragma("unroll") for (int m = 0; m < 4; ++m) _Pragma("unroll") for (int k = 0; k < 2; ++k) dst[m][k] = *(const PG8_LAS bf16x8*)(lds + PG8_SA(b, h) + aoff + m * 2048 + k * 1024); } while (0)
; #define PG8_MMA(ai, bj, At, Bt) do { __builtin_amdgcn_s_setprio(1); _Pragma("unroll") for (int m = 0; m < 4; ++m) _Pragma("unroll") for (int n = 0; n < 2; ++n) _Pragma("unroll") for (int k = 0; k < 2; ++k) \
;         acc[ai][bj][m][n] = __builtin_amdgcn_mfma_f32_16x16x32_bf16(Bt[n][k], At[m][k], acc[ai][bj][m][n], 0, 0, 0); __builtin_amdgcn_s_setprio(0); } while (0)
; #define PG8_WAIT_V(n) asm volatile("s_waitcnt vmcnt(" #n ")" ::: "memory")
; #define PG8_WAIT_L(n) asm volatile("s_waitcnt lgkmcnt(" #n ")" ::: "memory")
; #define PG8_BAR __builtin_amdgcn_s_barrier()
; #define PG8_SCHED __builtin_amdgcn_sched_barrier(0)
; template <class Epi, class Sched, bool ALIGN_EPI = false, bool SP2 = false>
; __device__ __forceinline__ void gemm_phase(PG8_LAS unsigned char* lds, const Gemm g, const Sched& S, const Epi& E) {
;     ...
;         for (int t = 0; t < nt; t += 2) {
;     ...
;             PG8_LDA(At, 1, 1); PG8_STAGE(PG8_SB(1, 0), b3, voffB); PG8_STAGE(PG8_SB(1, 1), b3 + hstepB, voffB); PG8_STAGE(PG8_SA(1, 0), a3, voffA);
;             PG8_WAIT_V(8); PG8_WAIT_L(0); PG8_BAR; PG8_MMA(1, 0, At, B0); PG8_MMA(1, 1, At, B1); PG8_BAR; PG8_SCHED;
	s_add_i32 s28, s34, s38
	v_lshl_add_u64 v[154:155], v[154:155], 0, s[14:15]
	s_mov_b32 m0, s28
	ds_read_b128 v[190:193], v163 offset:49152
	ds_read_b128 v[194:197], v163 offset:50176
	ds_read_b128 v[198:201], v163 offset:51200
	ds_read_b128 v[202:205], v163 offset:52224
	ds_read_b128 v[206:209], v163 offset:53248
	ds_read_b128 v[210:213], v163 offset:54272
	ds_read_b128 v[214:217], v163 offset:55296
	ds_read_b128 v[218:221], v163 offset:56320
	global_load_lds_dwordx4 v[154:155], off
	s_add_i32 m0, s28, 0x2000
	s_add_u32 s26, s26, 0x80080
	v_lshl_add_u64 v[154:155], v[222:223], 0, s[14:15]
	s_addc_u32 s27, s27, 0
	s_add_i32 s28, s35, s38
	global_load_lds_dwordx4 v[154:155], off
	v_lshl_add_u64 v[154:155], s[26:27], 0, v[130:131]
	s_mov_b32 m0, s28
	s_nop 0
	global_load_lds_dwordx4 v[154:155], off
	v_lshl_add_u64 v[154:155], s[26:27], 0, v[134:135]
	s_add_i32 m0, s28, 0x2000
	s_nop 0
	global_load_lds_dwordx4 v[154:155], off
	v_lshl_add_u64 v[154:155], v[224:225], 0, s[14:15]
	s_mov_b32 m0, s47
	s_nop 0
	global_load_lds_dwordx4 v[154:155], off
	v_lshl_add_u64 v[154:155], v[226:227], 0, s[14:15]
	s_mov_b32 m0, s48
	s_nop 0
	global_load_lds_dwordx4 v[154:155], off
	s_waitcnt vmcnt(8)
	s_waitcnt lgkmcnt(0)
	s_barrier
	s_setprio 1
	s_waitcnt lgkmcnt(0)
	v_mfma_f32_16x16x32_bf16 v[60:63], v[146:149], v[190:193], v[60:63]
	v_mfma_f32_16x16x32_bf16 v[56:59], v[166:169], v[190:193], v[56:59]
	v_mfma_f32_16x16x32_bf16 v[44:47], v[146:149], v[198:201], v[44:47]
	v_mfma_f32_16x16x32_bf16 v[40:43], v[166:169], v[198:201], v[40:43]
	v_mfma_f32_16x16x32_bf16 v[28:31], v[146:149], v[206:209], v[28:31]
	v_mfma_f32_16x16x32_bf16 v[24:27], v[166:169], v[206:209], v[24:27]
	v_mfma_f32_16x16x32_bf16 v[12:15], v[146:149], v[214:217], v[12:15]
	v_mfma_f32_16x16x32_bf16 v[8:11], v[166:169], v[214:217], v[8:11]
	v_mfma_f32_16x16x32_bf16 v[60:63], v[150:153], v[194:197], v[60:63]
	v_mfma_f32_16x16x32_bf16 v[56:59], v[170:173], v[194:197], v[56:59]
	v_mfma_f32_16x16x32_bf16 v[44:47], v[150:153], v[202:205], v[44:47]
	v_mfma_f32_16x16x32_bf16 v[40:43], v[170:173], v[202:205], v[40:43]
	v_mfma_f32_16x16x32_bf16 v[28:31], v[150:153], v[210:213], v[28:31]
	v_mfma_f32_16x16x32_bf16 v[24:27], v[170:173], v[210:213], v[24:27]
	v_mfma_f32_16x16x32_bf16 v[12:15], v[150:153], v[218:221], v[12:15]
	v_mfma_f32_16x16x32_bf16 v[8:11], v[170:173], v[218:221], v[8:11]
	v_mfma_f32_16x16x32_bf16 v[52:55], v[174:177], v[190:193], v[52:55]
	v_mfma_f32_16x16x32_bf16 v[48:51], v[182:185], v[190:193], v[48:51]
	v_mfma_f32_16x16x32_bf16 v[36:39], v[174:177], v[198:201], v[36:39]
	v_mfma_f32_16x16x32_bf16 v[32:35], v[182:185], v[198:201], v[32:35]
	v_mfma_f32_16x16x32_bf16 v[20:23], v[174:177], v[206:209], v[20:23]
	v_mfma_f32_16x16x32_bf16 v[16:19], v[182:185], v[206:209], v[16:19]
	v_mfma_f32_16x16x32_bf16 v[4:7], v[174:177], v[214:217], v[4:7]
	v_mfma_f32_16x16x32_bf16 v[0:3], v[182:185], v[214:217], v[0:3]
	v_mfma_f32_16x16x32_bf16 v[52:55], v[178:181], v[194:197], v[52:55]
	v_mfma_f32_16x16x32_bf16 v[48:51], v[186:189], v[194:197], v[48:51]
	v_mfma_f32_16x16x32_bf16 v[36:39], v[178:181], v[202:205], v[36:39]
	v_mfma_f32_16x16x32_bf16 v[32:35], v[186:189], v[202:205], v[32:35]
	v_mfma_f32_16x16x32_bf16 v[20:23], v[178:181], v[210:213], v[20:23]
	v_mfma_f32_16x16x32_bf16 v[16:19], v[186:189], v[210:213], v[16:19]
	v_mfma_f32_16x16x32_bf16 v[4:7], v[178:181], v[218:221], v[4:7]
	v_mfma_f32_16x16x32_bf16 v[0:3], v[186:189], v[218:221], v[0:3]
	s_add_i32 s31, s31, 2
	s_add_u32 s6, s6, 0x100
	s_addc_u32 s7, s7, 0
	s_add_u32 s21, s21, 0x100
	s_addc_u32 s30, s30, 0
	s_cmp_gt_u32 s31, 29
	s_setprio 0
	s_barrier
	s_cbranch_scc0 .LBB0_122
	s_and_b64 vcc, exec, s[16:17]
	s_cbranch_vccz .LBB0_125
	s_barrier

; #define PG8_STAGE(bufoff, gbase, voff) do { _Pragma("unroll") for (int _i = 0; _i < 2; ++_i) \
;         __builtin_amdgcn_global_load_lds((const unsigned*)((const char*)(gbase) + (voff)[_i]), (PG8_LAS unsigned*)(lds + (bufoff) + ldsw + _i * 8192), 16, 0, 0); } while (0)
; #define PG8_LDA(dst, b, h) do { _Pragma("unroll") for (int m = 0; m < 4; ++m) _Pragma("unroll") for (int k = 0; k < 2; ++k) dst[m][k] = *(const PG8_LAS bf16x8*)(lds + PG8_SA(b, h) + aoff + m * 2048 + k * 1024); } while (0)
; #define PG8_LDB(dst, b, h) do { _Pragma("unroll") for (int n = 0; n < 2; ++n) _Pragma("unroll") for (int k = 0; k < 2; ++k) dst[n][k] = *(const PG8_LAS bf16x8*)(lds + PG8_SB(b, h) + boff + n * 2048 + k * 1024); } while (0)
; #define PG8_MMA(ai, bj, At, Bt) do { __builtin_amdgcn_s_setprio(1); _Pragma("unroll") for (int m = 0; m < 4; ++m) _Pragma("unroll") for (int n = 0; n < 2; ++n) _Pragma("unroll") for (int k = 0; k < 2; ++k) \
;         acc[ai][bj][m][n] = __builtin_amdgcn_mfma_f32_16x16x32_bf16(Bt[n][k], At[m][k], acc[ai][bj][m][n], 0, 0, 0); __builtin_amdgcn_s_setprio(0); } while (0)
; #define PG8_WAIT_V(n) asm volatile("s_waitcnt vmcnt(" #n ")" ::: "memory")
; #define PG8_WAIT_L(n) asm volatile("s_waitcnt lgkmcnt(" #n ")" ::: "memory")
; #define PG8_BAR __builtin_amdgcn_s_barrier()
; #define PG8_SCHED __builtin_amdgcn_sched_barrier(0)
; template <class Epi, class Sched, bool ALIGN_EPI = false, bool SP2 = false>
; __device__ __forceinline__ void gemm_phase(PG8_LAS unsigned char* lds, const Gemm g, const Sched& S, const Epi& E) {
;     ...
;             PG8_LDB(B0, 0, 0); PG8_LDB(B1, 0, 1); PG8_SCHED; PG8_LDA(At, 0, 0); PG8_STAGE(PG8_SA(1, 1), a1 + hstepA, voffA);
;             PG8_WAIT_V(8); PG8_WAIT_L(0); PG8_BAR; PG8_MMA(0, 0, At, B0); PG8_MMA(0, 1, At, B1); PG8_BAR; PG8_SCHED;
.LBB0_632:
	ds_read_b128 v[144:147], v163
	ds_read_b128 v[166:169], v163 offset:1024
	ds_read_b128 v[170:173], v163 offset:2048
	ds_read_b128 v[174:177], v163 offset:3072
	ds_read_b128 v[178:181], v164
	ds_read_b128 v[182:185], v164 offset:1024
	ds_read_b128 v[186:189], v164 offset:2048
	ds_read_b128 v[190:193], v164 offset:3072
	s_add_u32 s46, s44, 0xfff00080
	s_addc_u32 s47, s45, -1
	s_cmp_eq_u32 s70, 28
	s_cselect_b32 s49, s37, s47
	s_cselect_b32 s48, s66, s46
	s_cselect_b32 s47, s35, s69
	s_cselect_b32 s46, s67, s68
	v_lshl_add_u64 v[148:149], s[44:45], 0, v[136:137]
	s_add_i32 m0, s43, 0xc000
	ds_read_b128 v[194:197], v165
	ds_read_b128 v[198:201], v165 offset:1024
	ds_read_b128 v[202:205], v165 offset:2048
	ds_read_b128 v[206:209], v165 offset:3072
	ds_read_b128 v[210:213], v165 offset:4096
	ds_read_b128 v[214:217], v165 offset:5120
	ds_read_b128 v[218:221], v165 offset:6144
	ds_read_b128 v[222:225], v165 offset:7168
	global_load_lds_dwordx4 v[148:149], off
	v_lshl_add_u64 v[148:149], s[44:45], 0, v[138:139]
	s_add_i32 m0, s43, 0xe000
	s_nop 0
	global_load_lds_dwordx4 v[148:149], off
	s_waitcnt vmcnt(8)
	s_waitcnt lgkmcnt(0)
	s_barrier
	s_setprio 1
	s_waitcnt lgkmcnt(0)
	v_mfma_f32_16x16x32_bf16 v[124:127], v[144:147], v[194:197], v[124:127]
	v_mfma_f32_16x16x32_bf16 v[120:123], v[170:173], v[194:197], v[120:123]
	v_mfma_f32_16x16x32_bf16 v[108:111], v[144:147], v[202:205], v[108:111]
	v_mfma_f32_16x16x32_bf16 v[104:107], v[170:173], v[202:205], v[104:107]
	v_mfma_f32_16x16x32_bf16 v[92:95], v[144:147], v[210:213], v[92:95]
	v_mfma_f32_16x16x32_bf16 v[88:91], v[170:173], v[210:213], v[88:91]
	v_mfma_f32_16x16x32_bf16 v[76:79], v[144:147], v[218:221], v[76:79]
	v_mfma_f32_16x16x32_bf16 v[72:75], v[170:173], v[218:221], v[72:75]
	v_mfma_f32_16x16x32_bf16 v[124:127], v[166:169], v[198:201], v[124:127]
	v_mfma_f32_16x16x32_bf16 v[120:123], v[174:177], v[198:201], v[120:123]
	v_mfma_f32_16x16x32_bf16 v[108:111], v[166:169], v[206:209], v[108:111]
	v_mfma_f32_16x16x32_bf16 v[104:107], v[174:177], v[206:209], v[104:107]
	v_mfma_f32_16x16x32_bf16 v[92:95], v[166:169], v[214:217], v[92:95]
	v_mfma_f32_16x16x32_bf16 v[88:91], v[174:177], v[214:217], v[88:91]
	v_mfma_f32_16x16x32_bf16 v[76:79], v[166:169], v[222:225], v[76:79]
	v_mfma_f32_16x16x32_bf16 v[72:75], v[174:177], v[222:225], v[72:75]
	v_mfma_f32_16x16x32_bf16 v[116:119], v[178:181], v[194:197], v[116:119]
	v_mfma_f32_16x16x32_bf16 v[112:115], v[186:189], v[194:197], v[112:115]
	v_mfma_f32_16x16x32_bf16 v[100:103], v[178:181], v[202:205], v[100:103]
	v_mfma_f32_16x16x32_bf16 v[96:99], v[186:189], v[202:205], v[96:99]
	v_mfma_f32_16x16x32_bf16 v[84:87], v[178:181], v[210:213], v[84:87]
	v_mfma_f32_16x16x32_bf16 v[80:83], v[186:189], v[210:213], v[80:83]
	v_mfma_f32_16x16x32_bf16 v[68:71], v[178:181], v[218:221], v[68:71]
	v_mfma_f32_16x16x32_bf16 v[64:67], v[186:189], v[218:221], v[64:67]
	v_mfma_f32_16x16x32_bf16 v[116:119], v[182:185], v[198:201], v[116:119]
	v_mfma_f32_16x16x32_bf16 v[112:115], v[190:193], v[198:201], v[112:115]
	v_mfma_f32_16x16x32_bf16 v[100:103], v[182:185], v[206:209], v[100:103]
	v_mfma_f32_16x16x32_bf16 v[96:99], v[190:193], v[206:209], v[96:99]
	v_mfma_f32_16x16x32_bf16 v[84:87], v[182:185], v[214:217], v[84:87]
	v_mfma_f32_16x16x32_bf16 v[80:83], v[190:193], v[214:217], v[80:83]
	v_mfma_f32_16x16x32_bf16 v[68:71], v[182:185], v[222:225], v[68:71]
	v_mfma_f32_16x16x32_bf16 v[64:67], v[190:193], v[222:225], v[64:67]
	s_setprio 0
	s_barrier
	s_add_i32 s71, s63, s55
	v_lshl_add_u64 v[148:149], s[46:47], 0, v[130:131]
	s_mov_b32 m0, s71
	ds_read_b128 v[194:197], v165 offset:16384
	ds_read_b128 v[198:201], v165 offset:17408
	ds_read_b128 v[202:205], v165 offset:18432
	ds_read_b128 v[206:209], v165 offset:19456
	ds_read_b128 v[210:213], v165 offset:20480
	ds_read_b128 v[214:217], v165 offset:21504
	ds_read_b128 v[218:221], v165 offset:22528
	ds_read_b128 v[222:225], v165 offset:23552
	global_load_lds_dwordx4 v[148:149], off
	s_add_i32 m0, s71, 0x2000
	s_add_u32 s72, s46, 0x80000
	v_lshl_add_u64 v[226:227], s[46:47], 0, v[134:135]
	s_addc_u32 s73, s47, 0
	s_add_i32 s71, s64, s55
	global_load_lds_dwordx4 v[226:227], off
	v_lshl_add_u64 v[228:229], s[72:73], 0, v[130:131]
	s_mov_b32 m0, s71
	v_lshl_add_u64 v[230:231], s[48:49], 0, v[132:133]
	global_load_lds_dwordx4 v[228:229], off
	v_lshl_add_u64 v[228:229], s[72:73], 0, v[134:135]
	s_add_i32 m0, s71, 0x2000
	s_nop 0
	global_load_lds_dwordx4 v[228:229], off
	v_lshl_add_u64 v[228:229], s[48:49], 0, v[128:129]
	s_mov_b32 m0, s43
	s_nop 0
	global_load_lds_dwordx4 v[228:229], off
	s_mov_b32 m0, s56
	s_nop 0
	global_load_lds_dwordx4 v[230:231], off
	s_waitcnt vmcnt(8)
	s_waitcnt lgkmcnt(0)
	s_barrier
; #define PG8_STAGE(bufoff, gbase, voff) do { _Pragma("unroll") for (int _i = 0; _i < 2; ++_i) \
;         __builtin_amdgcn_global_load_lds((const unsigned*)((const char*)(gbase) + (voff)[_i]), (PG8_LAS unsigned*)(lds + (bufoff) + ldsw + _i * 8192), 16, 0, 0); } while (0)
; #define PG8_LDA(dst, b, h) do { _Pragma("unroll") for (int m = 0; m < 4; ++m) _Pragma("unroll") for (int k = 0; k < 2; ++k) dst[m][k] = *(const PG8_LAS bf16x8*)(lds + PG8_SA(b, h) + aoff + m * 2048 + k * 1024); } while (0)
; #define PG8_LDB(dst, b, h) do { _Pragma("unroll") for (int n = 0; n < 2; ++n) _Pragma("unroll") for (int k = 0; k < 2; ++k) dst[n][k] = *(const PG8_LAS bf16x8*)(lds + PG8_SB(b, h) + boff + n * 2048 + k * 1024); } while (0)
; #define PG8_MMA(ai, bj, At, Bt) do { __builtin_amdgcn_s_setprio(1); _Pragma("unroll") for (int m = 0; m < 4; ++m) _Pragma("unroll") for (int n = 0; n < 2; ++n) _Pragma("unroll") for (int k = 0; k < 2; ++k) \
;         acc[ai][bj][m][n] = __builtin_amdgcn_mfma_f32_16x16x32_bf16(Bt[n][k], At[m][k], acc[ai][bj][m][n], 0, 0, 0); __builtin_amdgcn_s_setprio(0); } while (0)
; #define PG8_WAIT_V(n) asm volatile("s_waitcnt vmcnt(" #n ")" ::: "memory")
; #define PG8_WAIT_L(n) asm volatile("s_waitcnt lgkmcnt(" #n ")" ::: "memory")
; #define PG8_BAR __builtin_amdgcn_s_barrier()
; #define PG8_SCHED __builtin_amdgcn_sched_barrier(0)
; template <class Epi, class Sched, bool ALIGN_EPI = false, bool SP2 = false>
; __device__ __forceinline__ void gemm_phase(PG8_LAS unsigned char* lds, const Gemm g, const Sched& S, const Epi& E) {
;     ...
;             PG8_WAIT_V(8); PG8_WAIT_L(0); PG8_BAR; PG8_MMA(1, 0, At, B0); PG8_MMA(1, 1, At, B1); PG8_BAR; PG8_SCHED;
;             PG8_LDB(B0, 1, 0); PG8_LDB(B1, 1, 1); PG8_SCHED; PG8_LDA(At, 1, 0); PG8_STAGE(PG8_SA(0, 1), a2 + hstepA, voffA);
;             PG8_WAIT_V(8); PG8_WAIT_L(0); PG8_BAR; PG8_MMA(0, 0, At, B0); PG8_MMA(0, 1, At, B1); PG8_BAR; PG8_SCHED;
	s_setprio 1
	s_waitcnt lgkmcnt(0)
	v_mfma_f32_16x16x32_bf16 v[60:63], v[144:147], v[194:197], v[60:63]
	v_mfma_f32_16x16x32_bf16 v[56:59], v[170:173], v[194:197], v[56:59]
	v_mfma_f32_16x16x32_bf16 v[44:47], v[144:147], v[202:205], v[44:47]
	v_mfma_f32_16x16x32_bf16 v[40:43], v[170:173], v[202:205], v[40:43]
	v_mfma_f32_16x16x32_bf16 v[28:31], v[144:147], v[210:213], v[28:31]
	v_mfma_f32_16x16x32_bf16 v[24:27], v[170:173], v[210:213], v[24:27]
	v_mfma_f32_16x16x32_bf16 v[12:15], v[144:147], v[218:221], v[12:15]
	v_mfma_f32_16x16x32_bf16 v[8:11], v[170:173], v[218:221], v[8:11]
	v_mfma_f32_16x16x32_bf16 v[60:63], v[166:169], v[198:201], v[60:63]
	v_mfma_f32_16x16x32_bf16 v[56:59], v[174:177], v[198:201], v[56:59]
	v_mfma_f32_16x16x32_bf16 v[44:47], v[166:169], v[206:209], v[44:47]
	v_mfma_f32_16x16x32_bf16 v[40:43], v[174:177], v[206:209], v[40:43]
	v_mfma_f32_16x16x32_bf16 v[28:31], v[166:169], v[214:217], v[28:31]
	v_mfma_f32_16x16x32_bf16 v[24:27], v[174:177], v[214:217], v[24:27]
	v_mfma_f32_16x16x32_bf16 v[12:15], v[166:169], v[222:225], v[12:15]
	v_mfma_f32_16x16x32_bf16 v[8:11], v[174:177], v[222:225], v[8:11]
	v_mfma_f32_16x16x32_bf16 v[52:55], v[178:181], v[194:197], v[52:55]
	v_mfma_f32_16x16x32_bf16 v[48:51], v[186:189], v[194:197], v[48:51]
	v_mfma_f32_16x16x32_bf16 v[36:39], v[178:181], v[202:205], v[36:39]
	v_mfma_f32_16x16x32_bf16 v[32:35], v[186:189], v[202:205], v[32:35]
	v_mfma_f32_16x16x32_bf16 v[20:23], v[178:181], v[210:213], v[20:23]
	v_mfma_f32_16x16x32_bf16 v[16:19], v[186:189], v[210:213], v[16:19]
	v_mfma_f32_16x16x32_bf16 v[4:7], v[178:181], v[218:221], v[4:7]
	v_mfma_f32_16x16x32_bf16 v[0:3], v[186:189], v[218:221], v[0:3]
	v_mfma_f32_16x16x32_bf16 v[52:55], v[182:185], v[198:201], v[52:55]
	v_mfma_f32_16x16x32_bf16 v[48:51], v[190:193], v[198:201], v[48:51]
	v_mfma_f32_16x16x32_bf16 v[36:39], v[182:185], v[206:209], v[36:39]
	v_mfma_f32_16x16x32_bf16 v[32:35], v[190:193], v[206:209], v[32:35]
	v_mfma_f32_16x16x32_bf16 v[20:23], v[182:185], v[214:217], v[20:23]
	v_mfma_f32_16x16x32_bf16 v[16:19], v[190:193], v[214:217], v[16:19]
	v_mfma_f32_16x16x32_bf16 v[4:7], v[182:185], v[222:225], v[4:7]
	v_mfma_f32_16x16x32_bf16 v[0:3], v[190:193], v[222:225], v[0:3]
	s_setprio 0
	s_barrier
	s_add_i32 s71, 0, 0x18000
	s_add_i32 s72, 0, 0x1c000
	v_add_u32_e32 v174, s71, v161
	v_add_u32_e32 v190, s72, v161
	ds_read_b128 v[144:147], v174
	ds_read_b128 v[166:169], v174 offset:1024
	ds_read_b128 v[170:173], v174 offset:2048
	ds_read_b128 v[174:177], v174 offset:3072
	ds_read_b128 v[178:181], v190
	ds_read_b128 v[182:185], v190 offset:1024
	ds_read_b128 v[186:189], v190 offset:2048
	ds_read_b128 v[190:193], v190 offset:3072
	s_add_u32 s48, s48, 0x100000
	s_addc_u32 s49, s49, 0
	s_mov_b32 m0, s57
	v_lshl_add_u64 v[232:233], s[48:49], 0, v[128:129]
	ds_read_b128 v[194:197], v165 offset:32768
	ds_read_b128 v[198:201], v165 offset:33792
	ds_read_b128 v[202:205], v165 offset:34816
	ds_read_b128 v[206:209], v165 offset:35840
	ds_read_b128 v[210:213], v165 offset:36864
	ds_read_b128 v[214:217], v165 offset:37888
	ds_read_b128 v[218:221], v165 offset:38912
	ds_read_b128 v[222:225], v165 offset:39936
	global_load_lds_dwordx4 v[232:233], off
	v_lshl_add_u64 v[232:233], s[48:49], 0, v[132:133]
	s_mov_b32 m0, s58
	s_nop 0
	global_load_lds_dwordx4 v[232:233], off
	s_waitcnt vmcnt(8)
	s_waitcnt lgkmcnt(0)
	s_barrier
	s_setprio 1
	s_waitcnt lgkmcnt(0)
	v_mfma_f32_16x16x32_bf16 v[124:127], v[144:147], v[194:197], v[124:127]
	v_mfma_f32_16x16x32_bf16 v[120:123], v[170:173], v[194:197], v[120:123]
	v_mfma_f32_16x16x32_bf16 v[108:111], v[144:147], v[202:205], v[108:111]
	v_mfma_f32_16x16x32_bf16 v[104:107], v[170:173], v[202:205], v[104:107]
	v_mfma_f32_16x16x32_bf16 v[92:95], v[144:147], v[210:213], v[92:95]
	v_mfma_f32_16x16x32_bf16 v[88:91], v[170:173], v[210:213], v[88:91]
	v_mfma_f32_16x16x32_bf16 v[76:79], v[144:147], v[218:221], v[76:79]
	v_mfma_f32_16x16x32_bf16 v[72:75], v[170:173], v[218:221], v[72:75]
	v_mfma_f32_16x16x32_bf16 v[124:127], v[166:169], v[198:201], v[124:127]
	v_mfma_f32_16x16x32_bf16 v[120:123], v[174:177], v[198:201], v[120:123]
	v_mfma_f32_16x16x32_bf16 v[108:111], v[166:169], v[206:209], v[108:111]
	v_mfma_f32_16x16x32_bf16 v[104:107], v[174:177], v[206:209], v[104:107]
	v_mfma_f32_16x16x32_bf16 v[92:95], v[166:169], v[214:217], v[92:95]
	v_mfma_f32_16x16x32_bf16 v[88:91], v[174:177], v[214:217], v[88:91]
	v_mfma_f32_16x16x32_bf16 v[76:79], v[166:169], v[222:225], v[76:79]
	v_mfma_f32_16x16x32_bf16 v[72:75], v[174:177], v[222:225], v[72:75]
	v_mfma_f32_16x16x32_bf16 v[116:119], v[178:181], v[194:197], v[116:119]
	v_mfma_f32_16x16x32_bf16 v[112:115], v[186:189], v[194:197], v[112:115]
	v_mfma_f32_16x16x32_bf16 v[100:103], v[178:181], v[202:205], v[100:103]
	v_mfma_f32_16x16x32_bf16 v[96:99], v[186:189], v[202:205], v[96:99]
	v_mfma_f32_16x16x32_bf16 v[84:87], v[178:181], v[210:213], v[84:87]
	v_mfma_f32_16x16x32_bf16 v[80:83], v[186:189], v[210:213], v[80:83]
	v_mfma_f32_16x16x32_bf16 v[68:71], v[178:181], v[218:221], v[68:71]
	v_mfma_f32_16x16x32_bf16 v[64:67], v[186:189], v[218:221], v[64:67]
	v_mfma_f32_16x16x32_bf16 v[116:119], v[182:185], v[198:201], v[116:119]
	v_mfma_f32_16x16x32_bf16 v[112:115], v[190:193], v[198:201], v[112:115]
	v_mfma_f32_16x16x32_bf16 v[100:103], v[182:185], v[206:209], v[100:103]
	v_mfma_f32_16x16x32_bf16 v[96:99], v[190:193], v[206:209], v[96:99]
	v_mfma_f32_16x16x32_bf16 v[84:87], v[182:185], v[214:217], v[84:87]
	v_mfma_f32_16x16x32_bf16 v[80:83], v[190:193], v[214:217], v[80:83]
	v_mfma_f32_16x16x32_bf16 v[68:71], v[182:185], v[222:225], v[68:71]
	v_mfma_f32_16x16x32_bf16 v[64:67], v[190:193], v[222:225], v[64:67]
	s_setprio 0
	s_barrier
; #define PG8_STAGE(bufoff, gbase, voff) do { _Pragma("unroll") for (int _i = 0; _i < 2; ++_i) \
;         __builtin_amdgcn_global_load_lds((const unsigned*)((const char*)(gbase) + (voff)[_i]), (PG8_LAS unsigned*)(lds + (bufoff) + ldsw + _i * 8192), 16, 0, 0); } while (0)
; #define PG8_LDA(dst, b, h) do { _Pragma("unroll") for (int m = 0; m < 4; ++m) _Pragma("unroll") for (int k = 0; k < 2; ++k) dst[m][k] = *(const PG8_LAS bf16x8*)(lds + PG8_SA(b, h) + aoff + m * 2048 + k * 1024); } while (0)
; #define PG8_MMA(ai, bj, At, Bt) do { __builtin_amdgcn_s_setprio(1); _Pragma("unroll") for (int m = 0; m < 4; ++m) _Pragma("unroll") for (int n = 0; n < 2; ++n) _Pragma("unroll") for (int k = 0; k < 2; ++k) \
;         acc[ai][bj][m][n] = __builtin_amdgcn_mfma_f32_16x16x32_bf16(Bt[n][k], At[m][k], acc[ai][bj][m][n], 0, 0, 0); __builtin_amdgcn_s_setprio(0); } while (0)
; #define PG8_WAIT_V(n) asm volatile("s_waitcnt vmcnt(" #n ")" ::: "memory")
; #define PG8_WAIT_L(n) asm volatile("s_waitcnt lgkmcnt(" #n ")" ::: "memory")
; #define PG8_BAR __builtin_amdgcn_s_barrier()
; #define PG8_SCHED __builtin_amdgcn_sched_barrier(0)
; template <class Epi, class Sched, bool ALIGN_EPI = false, bool SP2 = false>
; __device__ __forceinline__ void gemm_phase(PG8_LAS unsigned char* lds, const Gemm g, const Sched& S, const Epi& E) {
;     ...
;         for (int t = 0; t < nt; t += 2) {
;     ...
;             PG8_LDA(At, 1, 1); PG8_STAGE(PG8_SB(1, 0), b3, voffB); PG8_STAGE(PG8_SB(1, 1), b3 + hstepB, voffB); PG8_STAGE(PG8_SA(1, 0), a3, voffA);
;             PG8_WAIT_V(8); PG8_WAIT_L(0); PG8_BAR; PG8_MMA(1, 0, At, B0); PG8_MMA(1, 1, At, B1); PG8_BAR; PG8_SCHED;
	s_add_i32 s48, s71, s55
	v_lshl_add_u64 v[148:149], v[148:149], 0, s[14:15]
	s_mov_b32 m0, s48
	ds_read_b128 v[194:197], v165 offset:49152
	ds_read_b128 v[198:201], v165 offset:50176
	ds_read_b128 v[202:205], v165 offset:51200
	ds_read_b128 v[206:209], v165 offset:52224
	ds_read_b128 v[210:213], v165 offset:53248
	ds_read_b128 v[214:217], v165 offset:54272
	ds_read_b128 v[218:221], v165 offset:55296
	ds_read_b128 v[222:225], v165 offset:56320
	global_load_lds_dwordx4 v[148:149], off
	s_add_i32 m0, s48, 0x2000
	s_add_u32 s46, s46, 0x80080
	v_lshl_add_u64 v[148:149], v[226:227], 0, s[14:15]
	s_addc_u32 s47, s47, 0
	s_add_i32 s48, s72, s55
	global_load_lds_dwordx4 v[148:149], off
	v_lshl_add_u64 v[148:149], s[46:47], 0, v[130:131]
	s_mov_b32 m0, s48
	s_nop 0
	global_load_lds_dwordx4 v[148:149], off
	v_lshl_add_u64 v[148:149], s[46:47], 0, v[134:135]
	s_add_i32 m0, s48, 0x2000
	s_nop 0
	global_load_lds_dwordx4 v[148:149], off
	v_lshl_add_u64 v[148:149], v[228:229], 0, s[14:15]
	s_mov_b32 m0, s60
	s_nop 0
	global_load_lds_dwordx4 v[148:149], off
	v_lshl_add_u64 v[148:149], v[230:231], 0, s[14:15]
	s_mov_b32 m0, s61
	s_nop 0
	global_load_lds_dwordx4 v[148:149], off
	s_waitcnt vmcnt(8)
	s_waitcnt lgkmcnt(0)
	s_barrier
	s_setprio 1
	s_waitcnt lgkmcnt(0)
	v_mfma_f32_16x16x32_bf16 v[60:63], v[144:147], v[194:197], v[60:63]
	v_mfma_f32_16x16x32_bf16 v[56:59], v[170:173], v[194:197], v[56:59]
	v_mfma_f32_16x16x32_bf16 v[44:47], v[144:147], v[202:205], v[44:47]
	v_mfma_f32_16x16x32_bf16 v[40:43], v[170:173], v[202:205], v[40:43]
	v_mfma_f32_16x16x32_bf16 v[28:31], v[144:147], v[210:213], v[28:31]
	v_mfma_f32_16x16x32_bf16 v[24:27], v[170:173], v[210:213], v[24:27]
	v_mfma_f32_16x16x32_bf16 v[12:15], v[144:147], v[218:221], v[12:15]
	v_mfma_f32_16x16x32_bf16 v[8:11], v[170:173], v[218:221], v[8:11]
	v_mfma_f32_16x16x32_bf16 v[60:63], v[166:169], v[198:201], v[60:63]
	v_mfma_f32_16x16x32_bf16 v[56:59], v[174:177], v[198:201], v[56:59]
	v_mfma_f32_16x16x32_bf16 v[44:47], v[166:169], v[206:209], v[44:47]
	v_mfma_f32_16x16x32_bf16 v[40:43], v[174:177], v[206:209], v[40:43]
	v_mfma_f32_16x16x32_bf16 v[28:31], v[166:169], v[214:217], v[28:31]
	v_mfma_f32_16x16x32_bf16 v[24:27], v[174:177], v[214:217], v[24:27]
	v_mfma_f32_16x16x32_bf16 v[12:15], v[166:169], v[222:225], v[12:15]
	v_mfma_f32_16x16x32_bf16 v[8:11], v[174:177], v[222:225], v[8:11]
	v_mfma_f32_16x16x32_bf16 v[52:55], v[178:181], v[194:197], v[52:55]
	v_mfma_f32_16x16x32_bf16 v[48:51], v[186:189], v[194:197], v[48:51]
	v_mfma_f32_16x16x32_bf16 v[36:39], v[178:181], v[202:205], v[36:39]
	v_mfma_f32_16x16x32_bf16 v[32:35], v[186:189], v[202:205], v[32:35]
	v_mfma_f32_16x16x32_bf16 v[20:23], v[178:181], v[210:213], v[20:23]
	v_mfma_f32_16x16x32_bf16 v[16:19], v[186:189], v[210:213], v[16:19]
	v_mfma_f32_16x16x32_bf16 v[4:7], v[178:181], v[218:221], v[4:7]
	v_mfma_f32_16x16x32_bf16 v[0:3], v[186:189], v[218:221], v[0:3]
	v_mfma_f32_16x16x32_bf16 v[52:55], v[182:185], v[198:201], v[52:55]
	v_mfma_f32_16x16x32_bf16 v[48:51], v[190:193], v[198:201], v[48:51]
	v_mfma_f32_16x16x32_bf16 v[36:39], v[182:185], v[206:209], v[36:39]
	v_mfma_f32_16x16x32_bf16 v[32:35], v[190:193], v[206:209], v[32:35]
	v_mfma_f32_16x16x32_bf16 v[20:23], v[182:185], v[214:217], v[20:23]
	v_mfma_f32_16x16x32_bf16 v[16:19], v[190:193], v[214:217], v[16:19]
	v_mfma_f32_16x16x32_bf16 v[4:7], v[182:185], v[222:225], v[4:7]
	v_mfma_f32_16x16x32_bf16 v[0:3], v[190:193], v[222:225], v[0:3]
	s_add_i32 s70, s70, 2
	s_add_u32 s44, s44, 0x100
	s_addc_u32 s45, s45, 0
	s_add_u32 s68, s68, 0x100
	s_addc_u32 s69, s69, 0
	s_cmp_gt_u32 s70, 29
	s_setprio 0
	s_barrier
	s_cbranch_scc0 .LBB0_632
	s_and_b64 vcc, exec, s[16:17]
	s_cbranch_vccz .LBB0_635
	s_barrier

; #define PG8_STAGE(bufoff, gbase, voff) do { _Pragma("unroll") for (int _i = 0; _i < 2; ++_i) \
;         __builtin_amdgcn_global_load_lds((const unsigned*)((const char*)(gbase) + (voff)[_i]), (PG8_LAS unsigned*)(lds + (bufoff) + ldsw + _i * 8192), 16, 0, 0); } while (0)
; #define PG8_LDA(dst, b, h) do { _Pragma("unroll") for (int m = 0; m < 4; ++m) _Pragma("unroll") for (int k = 0; k < 2; ++k) dst[m][k] = *(const PG8_LAS bf16x8*)(lds + PG8_SA(b, h) + aoff + m * 2048 + k * 1024); } while (0)
; #define PG8_LDB(dst, b, h) do { _Pragma("unroll") for (int n = 0; n < 2; ++n) _Pragma("unroll") for (int k = 0; k < 2; ++k) dst[n][k] = *(const PG8_LAS bf16x8*)(lds + PG8_SB(b, h) + boff + n * 2048 + k * 1024); } while (0)
; #define PG8_MMA(ai, bj, At, Bt) do { __builtin_amdgcn_s_setprio(1); _Pragma("unroll") for (int m = 0; m < 4; ++m) _Pragma("unroll") for (int n = 0; n < 2; ++n) _Pragma("unroll") for (int k = 0; k < 2; ++k) \
;         acc[ai][bj][m][n] = __builtin_amdgcn_mfma_f32_16x16x32_bf16(Bt[n][k], At[m][k], acc[ai][bj][m][n], 0, 0, 0); __builtin_amdgcn_s_setprio(0); } while (0)
; #define PG8_WAIT_V(n) asm volatile("s_waitcnt vmcnt(" #n ")" ::: "memory")
; #define PG8_WAIT_L(n) asm volatile("s_waitcnt lgkmcnt(" #n ")" ::: "memory")
; template <class Epi, class Sched, bool ALIGN_EPI = false, bool SP2 = false>
; __device__ __forceinline__ void gemm_phase(PG8_LAS unsigned char* lds, const Gemm g, const Sched& S, const Epi& E) {
;     ...
;             const bool last = (t == nt - 2);
;             const char* a1 = cA + (size_t)(t + 1) * kstep;
;             const char* a2 = last ? nA : cA + (size_t)(t + 2) * kstep; const char* b2 = last ? nB : cB + (size_t)(t + 2) * kstep;
;             const char* a3 = a2 + kstep; const char* b3 = b2 + kstep;
;             if (last && has_next) S.a_ready(nxt);
;             if constexpr (SP2) {
;             PG8_LDB(B0, 0, 0); PG8_LDB(B1, 0, 1); PG8_SCHED; PG8_LDA(At, 0, 0); PG8_STAGE(PG8_SA(1, 1), a1 + hstepA, voffA);
;             PG8_WAIT_V(8); PG8_WAIT_L(0); PG8_BAR; PG8_MMA(0, 0, At, B0); PG8_MMA(0, 1, At, B1); PG8_BAR; PG8_SCHED;
;             PG8_LDA(At, 0, 1); PG8_STAGE(PG8_SB(0, 0), b2, voffB); PG8_STAGE(PG8_SB(0, 1), b2 + hstepB, voffB); PG8_STAGE(PG8_SA(0, 0), a2, voffA);
;             PG8_WAIT_V(8); PG8_WAIT_L(0); PG8_BAR; PG8_MMA(1, 0, At, B0); PG8_MMA(1, 1, At, B1); PG8_BAR; PG8_SCHED;
.LBB0_656:
	ds_read_b128 v[144:147], v150
	ds_read_b128 v[162:165], v150 offset:1024
	ds_read_b128 v[166:169], v150 offset:2048
	ds_read_b128 v[170:173], v150 offset:3072
	ds_read_b128 v[174:177], v151
	ds_read_b128 v[178:181], v151 offset:1024
	ds_read_b128 v[182:185], v151 offset:2048
	ds_read_b128 v[186:189], v151 offset:3072
	s_add_u32 s44, s42, 0xfff00080
	s_addc_u32 s45, s43, -1
	s_cmp_eq_u32 s68, 28
	s_cselect_b32 s47, s37, s45
	s_cselect_b32 s46, s64, s44
	s_cselect_b32 s45, s35, s67
	s_cselect_b32 s44, s65, s66
	v_lshl_add_u64 v[148:149], s[42:43], 0, v[136:137]
	s_add_i32 m0, s3, 0xc000
	ds_read_b128 v[190:193], v152
	ds_read_b128 v[194:197], v152 offset:1024
	ds_read_b128 v[198:201], v152 offset:2048
	ds_read_b128 v[202:205], v152 offset:3072
	ds_read_b128 v[206:209], v152 offset:4096
	ds_read_b128 v[210:213], v152 offset:5120
	ds_read_b128 v[214:217], v152 offset:6144
	ds_read_b128 v[218:221], v152 offset:7168
	global_load_lds_dwordx4 v[148:149], off
	v_lshl_add_u64 v[148:149], s[42:43], 0, v[138:139]
	s_add_i32 m0, s3, 0xe000
	s_nop 0
	global_load_lds_dwordx4 v[148:149], off
	s_waitcnt vmcnt(8)
	s_waitcnt lgkmcnt(0)
	s_barrier
	s_setprio 1
	s_waitcnt lgkmcnt(0)
	v_mfma_f32_16x16x32_bf16 v[124:127], v[144:147], v[190:193], v[124:127]
	v_mfma_f32_16x16x32_bf16 v[120:123], v[166:169], v[190:193], v[120:123]
	v_mfma_f32_16x16x32_bf16 v[108:111], v[144:147], v[198:201], v[108:111]
	v_mfma_f32_16x16x32_bf16 v[104:107], v[166:169], v[198:201], v[104:107]
	v_mfma_f32_16x16x32_bf16 v[92:95], v[144:147], v[206:209], v[92:95]
	v_mfma_f32_16x16x32_bf16 v[88:91], v[166:169], v[206:209], v[88:91]
	v_mfma_f32_16x16x32_bf16 v[76:79], v[144:147], v[214:217], v[76:79]
	v_mfma_f32_16x16x32_bf16 v[72:75], v[166:169], v[214:217], v[72:75]
	v_mfma_f32_16x16x32_bf16 v[124:127], v[162:165], v[194:197], v[124:127]
	v_mfma_f32_16x16x32_bf16 v[120:123], v[170:173], v[194:197], v[120:123]
	v_mfma_f32_16x16x32_bf16 v[108:111], v[162:165], v[202:205], v[108:111]
	v_mfma_f32_16x16x32_bf16 v[104:107], v[170:173], v[202:205], v[104:107]
	v_mfma_f32_16x16x32_bf16 v[92:95], v[162:165], v[210:213], v[92:95]
	v_mfma_f32_16x16x32_bf16 v[88:91], v[170:173], v[210:213], v[88:91]
	v_mfma_f32_16x16x32_bf16 v[76:79], v[162:165], v[218:221], v[76:79]
	v_mfma_f32_16x16x32_bf16 v[72:75], v[170:173], v[218:221], v[72:75]
	v_mfma_f32_16x16x32_bf16 v[116:119], v[174:177], v[190:193], v[116:119]
	v_mfma_f32_16x16x32_bf16 v[112:115], v[182:185], v[190:193], v[112:115]
	v_mfma_f32_16x16x32_bf16 v[100:103], v[174:177], v[198:201], v[100:103]
	v_mfma_f32_16x16x32_bf16 v[96:99], v[182:185], v[198:201], v[96:99]
	v_mfma_f32_16x16x32_bf16 v[84:87], v[174:177], v[206:209], v[84:87]
	v_mfma_f32_16x16x32_bf16 v[80:83], v[182:185], v[206:209], v[80:83]
	v_mfma_f32_16x16x32_bf16 v[68:71], v[174:177], v[214:217], v[68:71]
	v_mfma_f32_16x16x32_bf16 v[64:67], v[182:185], v[214:217], v[64:67]
	v_mfma_f32_16x16x32_bf16 v[116:119], v[178:181], v[194:197], v[116:119]
	v_mfma_f32_16x16x32_bf16 v[112:115], v[186:189], v[194:197], v[112:115]
	v_mfma_f32_16x16x32_bf16 v[100:103], v[178:181], v[202:205], v[100:103]
	v_mfma_f32_16x16x32_bf16 v[96:99], v[186:189], v[202:205], v[96:99]
	v_mfma_f32_16x16x32_bf16 v[84:87], v[178:181], v[210:213], v[84:87]
	v_mfma_f32_16x16x32_bf16 v[80:83], v[186:189], v[210:213], v[80:83]
	v_mfma_f32_16x16x32_bf16 v[68:71], v[178:181], v[218:221], v[68:71]
	v_mfma_f32_16x16x32_bf16 v[64:67], v[186:189], v[218:221], v[64:67]
	s_setprio 0
	s_barrier
	s_add_i32 s69, s61, s51
	v_lshl_add_u64 v[148:149], s[44:45], 0, v[130:131]
	s_mov_b32 m0, s69
	ds_read_b128 v[190:193], v152 offset:16384
	ds_read_b128 v[194:197], v152 offset:17408
	ds_read_b128 v[198:201], v152 offset:18432
	ds_read_b128 v[202:205], v152 offset:19456
	ds_read_b128 v[206:209], v152 offset:20480
	ds_read_b128 v[210:213], v152 offset:21504
	ds_read_b128 v[214:217], v152 offset:22528
	ds_read_b128 v[218:221], v152 offset:23552
	global_load_lds_dwordx4 v[148:149], off
	s_add_i32 m0, s69, 0x2000
	s_add_u32 s70, s44, 0x80000
	v_lshl_add_u64 v[158:159], s[44:45], 0, v[134:135]
	s_addc_u32 s71, s45, 0
	s_add_i32 s69, s62, s51
	global_load_lds_dwordx4 v[158:159], off
	v_lshl_add_u64 v[222:223], s[70:71], 0, v[130:131]
	s_mov_b32 m0, s69
	v_lshl_add_u64 v[224:225], s[46:47], 0, v[132:133]
	global_load_lds_dwordx4 v[222:223], off
	v_lshl_add_u64 v[222:223], s[70:71], 0, v[134:135]
	s_add_i32 m0, s69, 0x2000
	s_nop 0
	global_load_lds_dwordx4 v[222:223], off
	v_lshl_add_u64 v[222:223], s[46:47], 0, v[128:129]
	s_mov_b32 m0, s3
	s_nop 0
	global_load_lds_dwordx4 v[222:223], off
	s_mov_b32 m0, s54
	s_nop 0
	global_load_lds_dwordx4 v[224:225], off
	s_waitcnt vmcnt(8)
	s_waitcnt lgkmcnt(0)
	s_barrier
; #define PG8_STAGE(bufoff, gbase, voff) do { _Pragma("unroll") for (int _i = 0; _i < 2; ++_i) \
;         __builtin_amdgcn_global_load_lds((const unsigned*)((const char*)(gbase) + (voff)[_i]), (PG8_LAS unsigned*)(lds + (bufoff) + ldsw + _i * 8192), 16, 0, 0); } while (0)
; #define PG8_LDA(dst, b, h) do { _Pragma("unroll") for (int m = 0; m < 4; ++m) _Pragma("unroll") for (int k = 0; k < 2; ++k) dst[m][k] = *(const PG8_LAS bf16x8*)(lds + PG8_SA(b, h) + aoff + m * 2048 + k * 1024); } while (0)
; #define PG8_LDB(dst, b, h) do { _Pragma("unroll") for (int n = 0; n < 2; ++n) _Pragma("unroll") for (int k = 0; k < 2; ++k) dst[n][k] = *(const PG8_LAS bf16x8*)(lds + PG8_SB(b, h) + boff + n * 2048 + k * 1024); } while (0)
; #define PG8_MMA(ai, bj, At, Bt) do { __builtin_amdgcn_s_setprio(1); _Pragma("unroll") for (int m = 0; m < 4; ++m) _Pragma("unroll") for (int n = 0; n < 2; ++n) _Pragma("unroll") for (int k = 0; k < 2; ++k) \
;         acc[ai][bj][m][n] = __builtin_amdgcn_mfma_f32_16x16x32_bf16(Bt[n][k], At[m][k], acc[ai][bj][m][n], 0, 0, 0); __builtin_amdgcn_s_setprio(0); } while (0)
; #define PG8_WAIT_V(n) asm volatile("s_waitcnt vmcnt(" #n ")" ::: "memory")
; #define PG8_WAIT_L(n) asm volatile("s_waitcnt lgkmcnt(" #n ")" ::: "memory")
; #define PG8_BAR __builtin_amdgcn_s_barrier()
; #define PG8_SCHED __builtin_amdgcn_sched_barrier(0)
; template <class Epi, class Sched, bool ALIGN_EPI = false, bool SP2 = false>
; __device__ __forceinline__ void gemm_phase(PG8_LAS unsigned char* lds, const Gemm g, const Sched& S, const Epi& E) {
;     ...
;             PG8_WAIT_V(8); PG8_WAIT_L(0); PG8_BAR; PG8_MMA(1, 0, At, B0); PG8_MMA(1, 1, At, B1); PG8_BAR; PG8_SCHED;
;             PG8_LDB(B0, 1, 0); PG8_LDB(B1, 1, 1); PG8_SCHED; PG8_LDA(At, 1, 0); PG8_STAGE(PG8_SA(0, 1), a2 + hstepA, voffA);
;             PG8_WAIT_V(8); PG8_WAIT_L(0); PG8_BAR; PG8_MMA(0, 0, At, B0); PG8_MMA(0, 1, At, B1); PG8_BAR; PG8_SCHED;
	s_setprio 1
	s_waitcnt lgkmcnt(0)
	v_mfma_f32_16x16x32_bf16 v[60:63], v[144:147], v[190:193], v[60:63]
	v_mfma_f32_16x16x32_bf16 v[56:59], v[166:169], v[190:193], v[56:59]
	v_mfma_f32_16x16x32_bf16 v[44:47], v[144:147], v[198:201], v[44:47]
	v_mfma_f32_16x16x32_bf16 v[40:43], v[166:169], v[198:201], v[40:43]
	v_mfma_f32_16x16x32_bf16 v[28:31], v[144:147], v[206:209], v[28:31]
	v_mfma_f32_16x16x32_bf16 v[24:27], v[166:169], v[206:209], v[24:27]
	v_mfma_f32_16x16x32_bf16 v[12:15], v[144:147], v[214:217], v[12:15]
	v_mfma_f32_16x16x32_bf16 v[8:11], v[166:169], v[214:217], v[8:11]
	v_mfma_f32_16x16x32_bf16 v[60:63], v[162:165], v[194:197], v[60:63]
	v_mfma_f32_16x16x32_bf16 v[56:59], v[170:173], v[194:197], v[56:59]
	v_mfma_f32_16x16x32_bf16 v[44:47], v[162:165], v[202:205], v[44:47]
	v_mfma_f32_16x16x32_bf16 v[40:43], v[170:173], v[202:205], v[40:43]
	v_mfma_f32_16x16x32_bf16 v[28:31], v[162:165], v[210:213], v[28:31]
	v_mfma_f32_16x16x32_bf16 v[24:27], v[170:173], v[210:213], v[24:27]
	v_mfma_f32_16x16x32_bf16 v[12:15], v[162:165], v[218:221], v[12:15]
	v_mfma_f32_16x16x32_bf16 v[8:11], v[170:173], v[218:221], v[8:11]
	v_mfma_f32_16x16x32_bf16 v[52:55], v[174:177], v[190:193], v[52:55]
	v_mfma_f32_16x16x32_bf16 v[48:51], v[182:185], v[190:193], v[48:51]
	v_mfma_f32_16x16x32_bf16 v[36:39], v[174:177], v[198:201], v[36:39]
	v_mfma_f32_16x16x32_bf16 v[32:35], v[182:185], v[198:201], v[32:35]
	v_mfma_f32_16x16x32_bf16 v[20:23], v[174:177], v[206:209], v[20:23]
	v_mfma_f32_16x16x32_bf16 v[16:19], v[182:185], v[206:209], v[16:19]
	v_mfma_f32_16x16x32_bf16 v[4:7], v[174:177], v[214:217], v[4:7]
	v_mfma_f32_16x16x32_bf16 v[0:3], v[182:185], v[214:217], v[0:3]
	v_mfma_f32_16x16x32_bf16 v[52:55], v[178:181], v[194:197], v[52:55]
	v_mfma_f32_16x16x32_bf16 v[48:51], v[186:189], v[194:197], v[48:51]
	v_mfma_f32_16x16x32_bf16 v[36:39], v[178:181], v[202:205], v[36:39]
	v_mfma_f32_16x16x32_bf16 v[32:35], v[186:189], v[202:205], v[32:35]
	v_mfma_f32_16x16x32_bf16 v[20:23], v[178:181], v[210:213], v[20:23]
	v_mfma_f32_16x16x32_bf16 v[16:19], v[186:189], v[210:213], v[16:19]
	v_mfma_f32_16x16x32_bf16 v[4:7], v[178:181], v[218:221], v[4:7]
	v_mfma_f32_16x16x32_bf16 v[0:3], v[186:189], v[218:221], v[0:3]
	s_setprio 0
	s_barrier
	s_add_i32 s69, 0, 0x18000
	v_add_u32_e32 v154, s69, v155
	s_add_i32 s70, 0, 0x1c000
	ds_read_b128 v[144:147], v154
	ds_read_b128 v[162:165], v154 offset:1024
	ds_read_b128 v[166:169], v154 offset:2048
	ds_read_b128 v[170:173], v154 offset:3072
	v_add_u32_e32 v154, s70, v155
	ds_read_b128 v[174:177], v154
	ds_read_b128 v[178:181], v154 offset:1024
	ds_read_b128 v[182:185], v154 offset:2048
	ds_read_b128 v[186:189], v154 offset:3072
	s_add_u32 s46, s46, 0x100000
	s_addc_u32 s47, s47, 0
	s_mov_b32 m0, s55
	v_lshl_add_u64 v[226:227], s[46:47], 0, v[128:129]
	ds_read_b128 v[190:193], v152 offset:32768
	ds_read_b128 v[194:197], v152 offset:33792
	ds_read_b128 v[198:201], v152 offset:34816
	ds_read_b128 v[202:205], v152 offset:35840
	ds_read_b128 v[206:209], v152 offset:36864
	ds_read_b128 v[210:213], v152 offset:37888
	ds_read_b128 v[214:217], v152 offset:38912
	ds_read_b128 v[218:221], v152 offset:39936
	global_load_lds_dwordx4 v[226:227], off
	v_lshl_add_u64 v[226:227], s[46:47], 0, v[132:133]
	s_mov_b32 m0, s56
	s_nop 0
	global_load_lds_dwordx4 v[226:227], off
	s_waitcnt vmcnt(8)
	s_waitcnt lgkmcnt(0)
	s_barrier
	s_setprio 1
	s_waitcnt lgkmcnt(0)
	v_mfma_f32_16x16x32_bf16 v[124:127], v[144:147], v[190:193], v[124:127]
	v_mfma_f32_16x16x32_bf16 v[120:123], v[166:169], v[190:193], v[120:123]
	v_mfma_f32_16x16x32_bf16 v[108:111], v[144:147], v[198:201], v[108:111]
	v_mfma_f32_16x16x32_bf16 v[104:107], v[166:169], v[198:201], v[104:107]
	v_mfma_f32_16x16x32_bf16 v[92:95], v[144:147], v[206:209], v[92:95]
	v_mfma_f32_16x16x32_bf16 v[88:91], v[166:169], v[206:209], v[88:91]
	v_mfma_f32_16x16x32_bf16 v[76:79], v[144:147], v[214:217], v[76:79]
	v_mfma_f32_16x16x32_bf16 v[72:75], v[166:169], v[214:217], v[72:75]
	v_mfma_f32_16x16x32_bf16 v[124:127], v[162:165], v[194:197], v[124:127]
	v_mfma_f32_16x16x32_bf16 v[120:123], v[170:173], v[194:197], v[120:123]
	v_mfma_f32_16x16x32_bf16 v[108:111], v[162:165], v[202:205], v[108:111]
	v_mfma_f32_16x16x32_bf16 v[104:107], v[170:173], v[202:205], v[104:107]
	v_mfma_f32_16x16x32_bf16 v[92:95], v[162:165], v[210:213], v[92:95]
	v_mfma_f32_16x16x32_bf16 v[88:91], v[170:173], v[210:213], v[88:91]
	v_mfma_f32_16x16x32_bf16 v[76:79], v[162:165], v[218:221], v[76:79]
	v_mfma_f32_16x16x32_bf16 v[72:75], v[170:173], v[218:221], v[72:75]
	v_mfma_f32_16x16x32_bf16 v[116:119], v[174:177], v[190:193], v[116:119]
	v_mfma_f32_16x16x32_bf16 v[112:115], v[182:185], v[190:193], v[112:115]
	v_mfma_f32_16x16x32_bf16 v[100:103], v[174:177], v[198:201], v[100:103]
	v_mfma_f32_16x16x32_bf16 v[96:99], v[182:185], v[198:201], v[96:99]
	v_mfma_f32_16x16x32_bf16 v[84:87], v[174:177], v[206:209], v[84:87]
	v_mfma_f32_16x16x32_bf16 v[80:83], v[182:185], v[206:209], v[80:83]
	v_mfma_f32_16x16x32_bf16 v[68:71], v[174:177], v[214:217], v[68:71]
	v_mfma_f32_16x16x32_bf16 v[64:67], v[182:185], v[214:217], v[64:67]
	v_mfma_f32_16x16x32_bf16 v[116:119], v[178:181], v[194:197], v[116:119]
	v_mfma_f32_16x16x32_bf16 v[112:115], v[186:189], v[194:197], v[112:115]
	v_mfma_f32_16x16x32_bf16 v[100:103], v[178:181], v[202:205], v[100:103]
	v_mfma_f32_16x16x32_bf16 v[96:99], v[186:189], v[202:205], v[96:99]
	v_mfma_f32_16x16x32_bf16 v[84:87], v[178:181], v[210:213], v[84:87]
	v_mfma_f32_16x16x32_bf16 v[80:83], v[186:189], v[210:213], v[80:83]
	v_mfma_f32_16x16x32_bf16 v[68:71], v[178:181], v[218:221], v[68:71]
	v_mfma_f32_16x16x32_bf16 v[64:67], v[186:189], v[218:221], v[64:67]
	s_setprio 0
	s_barrier
; #define PG8_STAGE(bufoff, gbase, voff) do { _Pragma("unroll") for (int _i = 0; _i < 2; ++_i) \
;         __builtin_amdgcn_global_load_lds((const unsigned*)((const char*)(gbase) + (voff)[_i]), (PG8_LAS unsigned*)(lds + (bufoff) + ldsw + _i * 8192), 16, 0, 0); } while (0)
; #define PG8_LDA(dst, b, h) do { _Pragma("unroll") for (int m = 0; m < 4; ++m) _Pragma("unroll") for (int k = 0; k < 2; ++k) dst[m][k] = *(const PG8_LAS bf16x8*)(lds + PG8_SA(b, h) + aoff + m * 2048 + k * 1024); } while (0)
; #define PG8_MMA(ai, bj, At, Bt) do { __builtin_amdgcn_s_setprio(1); _Pragma("unroll") for (int m = 0; m < 4; ++m) _Pragma("unroll") for (int n = 0; n < 2; ++n) _Pragma("unroll") for (int k = 0; k < 2; ++k) \
;         acc[ai][bj][m][n] = __builtin_amdgcn_mfma_f32_16x16x32_bf16(Bt[n][k], At[m][k], acc[ai][bj][m][n], 0, 0, 0); __builtin_amdgcn_s_setprio(0); } while (0)
; #define PG8_WAIT_V(n) asm volatile("s_waitcnt vmcnt(" #n ")" ::: "memory")
; #define PG8_WAIT_L(n) asm volatile("s_waitcnt lgkmcnt(" #n ")" ::: "memory")
; #define PG8_BAR __builtin_amdgcn_s_barrier()
; #define PG8_SCHED __builtin_amdgcn_sched_barrier(0)
; template <class Epi, class Sched, bool ALIGN_EPI = false, bool SP2 = false>
; __device__ __forceinline__ void gemm_phase(PG8_LAS unsigned char* lds, const Gemm g, const Sched& S, const Epi& E) {
;     ...
;         for (int t = 0; t < nt; t += 2) {
;     ...
;             PG8_LDA(At, 1, 1); PG8_STAGE(PG8_SB(1, 0), b3, voffB); PG8_STAGE(PG8_SB(1, 1), b3 + hstepB, voffB); PG8_STAGE(PG8_SA(1, 0), a3, voffA);
;             PG8_WAIT_V(8); PG8_WAIT_L(0); PG8_BAR; PG8_MMA(1, 0, At, B0); PG8_MMA(1, 1, At, B1); PG8_BAR; PG8_SCHED;
	s_add_i32 s46, s69, s51
	v_lshl_add_u64 v[148:149], v[148:149], 0, s[14:15]
	s_mov_b32 m0, s46
	ds_read_b128 v[190:193], v152 offset:49152
	ds_read_b128 v[194:197], v152 offset:50176
	ds_read_b128 v[198:201], v152 offset:51200
	ds_read_b128 v[202:205], v152 offset:52224
	ds_read_b128 v[206:209], v152 offset:53248
	ds_read_b128 v[210:213], v152 offset:54272
	ds_read_b128 v[214:217], v152 offset:55296
	ds_read_b128 v[218:221], v152 offset:56320
	global_load_lds_dwordx4 v[148:149], off
	s_add_i32 m0, s46, 0x2000
	s_add_u32 s44, s44, 0x80080
	v_lshl_add_u64 v[148:149], v[158:159], 0, s[14:15]
	s_addc_u32 s45, s45, 0
	s_add_i32 s46, s70, s51
	global_load_lds_dwordx4 v[148:149], off
	v_lshl_add_u64 v[148:149], s[44:45], 0, v[130:131]
	s_mov_b32 m0, s46
	s_nop 0
	global_load_lds_dwordx4 v[148:149], off
	v_lshl_add_u64 v[148:149], s[44:45], 0, v[134:135]
	s_add_i32 m0, s46, 0x2000
	s_nop 0
	global_load_lds_dwordx4 v[148:149], off
	v_lshl_add_u64 v[148:149], v[222:223], 0, s[14:15]
	s_mov_b32 m0, s58
	s_nop 0
	global_load_lds_dwordx4 v[148:149], off
	v_lshl_add_u64 v[148:149], v[224:225], 0, s[14:15]
	s_mov_b32 m0, s59
	s_nop 0
	global_load_lds_dwordx4 v[148:149], off
	s_waitcnt vmcnt(8)
	s_waitcnt lgkmcnt(0)
	s_barrier
	s_setprio 1
	s_waitcnt lgkmcnt(0)
	v_mfma_f32_16x16x32_bf16 v[60:63], v[144:147], v[190:193], v[60:63]
	v_mfma_f32_16x16x32_bf16 v[56:59], v[166:169], v[190:193], v[56:59]
	v_mfma_f32_16x16x32_bf16 v[44:47], v[144:147], v[198:201], v[44:47]
	v_mfma_f32_16x16x32_bf16 v[40:43], v[166:169], v[198:201], v[40:43]
	v_mfma_f32_16x16x32_bf16 v[28:31], v[144:147], v[206:209], v[28:31]
	v_mfma_f32_16x16x32_bf16 v[24:27], v[166:169], v[206:209], v[24:27]
	v_mfma_f32_16x16x32_bf16 v[12:15], v[144:147], v[214:217], v[12:15]
	v_mfma_f32_16x16x32_bf16 v[8:11], v[166:169], v[214:217], v[8:11]
	v_mfma_f32_16x16x32_bf16 v[60:63], v[162:165], v[194:197], v[60:63]
	v_mfma_f32_16x16x32_bf16 v[56:59], v[170:173], v[194:197], v[56:59]
	v_mfma_f32_16x16x32_bf16 v[44:47], v[162:165], v[202:205], v[44:47]
	v_mfma_f32_16x16x32_bf16 v[40:43], v[170:173], v[202:205], v[40:43]
	v_mfma_f32_16x16x32_bf16 v[28:31], v[162:165], v[210:213], v[28:31]
	v_mfma_f32_16x16x32_bf16 v[24:27], v[170:173], v[210:213], v[24:27]
	v_mfma_f32_16x16x32_bf16 v[12:15], v[162:165], v[218:221], v[12:15]
	v_mfma_f32_16x16x32_bf16 v[8:11], v[170:173], v[218:221], v[8:11]
	v_mfma_f32_16x16x32_bf16 v[52:55], v[174:177], v[190:193], v[52:55]
	v_mfma_f32_16x16x32_bf16 v[48:51], v[182:185], v[190:193], v[48:51]
	v_mfma_f32_16x16x32_bf16 v[36:39], v[174:177], v[198:201], v[36:39]
	v_mfma_f32_16x16x32_bf16 v[32:35], v[182:185], v[198:201], v[32:35]
	v_mfma_f32_16x16x32_bf16 v[20:23], v[174:177], v[206:209], v[20:23]
	v_mfma_f32_16x16x32_bf16 v[16:19], v[182:185], v[206:209], v[16:19]
	v_mfma_f32_16x16x32_bf16 v[4:7], v[174:177], v[214:217], v[4:7]
	v_mfma_f32_16x16x32_bf16 v[0:3], v[182:185], v[214:217], v[0:3]
	v_mfma_f32_16x16x32_bf16 v[52:55], v[178:181], v[194:197], v[52:55]
	v_mfma_f32_16x16x32_bf16 v[48:51], v[186:189], v[194:197], v[48:51]
	v_mfma_f32_16x16x32_bf16 v[36:39], v[178:181], v[202:205], v[36:39]
	v_mfma_f32_16x16x32_bf16 v[32:35], v[186:189], v[202:205], v[32:35]
	v_mfma_f32_16x16x32_bf16 v[20:23], v[178:181], v[210:213], v[20:23]
	v_mfma_f32_16x16x32_bf16 v[16:19], v[186:189], v[210:213], v[16:19]
	v_mfma_f32_16x16x32_bf16 v[4:7], v[178:181], v[218:221], v[4:7]
	v_mfma_f32_16x16x32_bf16 v[0:3], v[186:189], v[218:221], v[0:3]
	s_add_i32 s68, s68, 2
	s_add_u32 s42, s42, 0x100
	s_addc_u32 s43, s43, 0
	s_add_u32 s66, s66, 0x100
	s_addc_u32 s67, s67, 0
	s_cmp_gt_u32 s68, 29
	s_setprio 0
	s_barrier
	s_cbranch_scc0 .LBB0_656
	s_and_b64 vcc, exec, s[16:17]
	s_cbranch_vccz .LBB0_659
	s_barrier

; #define PG8_STAGE(bufoff, gbase, voff) do { _Pragma("unroll") for (int _i = 0; _i < 2; ++_i) \
;         __builtin_amdgcn_global_load_lds((const unsigned*)((const char*)(gbase) + (voff)[_i]), (PG8_LAS unsigned*)(lds + (bufoff) + ldsw + _i * 8192), 16, 0, 0); } while (0)
; #define PG8_LDA(dst, b, h) do { _Pragma("unroll") for (int m = 0; m < 4; ++m) _Pragma("unroll") for (int k = 0; k < 2; ++k) dst[m][k] = *(const PG8_LAS bf16x8*)(lds + PG8_SA(b, h) + aoff + m * 2048 + k * 1024); } while (0)
; #define PG8_LDB(dst, b, h) do { _Pragma("unroll") for (int n = 0; n < 2; ++n) _Pragma("unroll") for (int k = 0; k < 2; ++k) dst[n][k] = *(const PG8_LAS bf16x8*)(lds + PG8_SB(b, h) + boff + n * 2048 + k * 1024); } while (0)
; #define PG8_MMA(ai, bj, At, Bt) do { __builtin_amdgcn_s_setprio(1); _Pragma("unroll") for (int m = 0; m < 4; ++m) _Pragma("unroll") for (int n = 0; n < 2; ++n) _Pragma("unroll") for (int k = 0; k < 2; ++k) \
;         acc[ai][bj][m][n] = __builtin_amdgcn_mfma_f32_16x16x32_bf16(Bt[n][k], At[m][k], acc[ai][bj][m][n], 0, 0, 0); __builtin_amdgcn_s_setprio(0); } while (0)
; #define PG8_WAIT_V(n) asm volatile("s_waitcnt vmcnt(" #n ")" ::: "memory")
; #define PG8_WAIT_L(n) asm volatile("s_waitcnt lgkmcnt(" #n ")" ::: "memory")
; template <class Epi, class Sched, bool ALIGN_EPI = false, bool SP2 = false>
; __device__ __forceinline__ void gemm_phase(PG8_LAS unsigned char* lds, const Gemm g, const Sched& S, const Epi& E) {
;     ...
;             const bool last = (t == nt - 2);
;             const char* a1 = cA + (size_t)(t + 1) * kstep;
;             const char* a2 = last ? nA : cA + (size_t)(t + 2) * kstep; const char* b2 = last ? nB : cB + (size_t)(t + 2) * kstep;
;             const char* a3 = a2 + kstep; const char* b3 = b2 + kstep;
;             if (last && has_next) S.a_ready(nxt);
;             if constexpr (SP2) {
;             PG8_LDB(B0, 0, 0); PG8_LDB(B1, 0, 1); PG8_SCHED; PG8_LDA(At, 0, 0); PG8_STAGE(PG8_SA(1, 1), a1 + hstepA, voffA);
;             PG8_WAIT_V(8); PG8_WAIT_L(0); PG8_BAR; PG8_MMA(0, 0, At, B0); PG8_MMA(0, 1, At, B1); PG8_BAR; PG8_SCHED;
;             PG8_LDA(At, 0, 1); PG8_STAGE(PG8_SB(0, 0), b2, voffB); PG8_STAGE(PG8_SB(0, 1), b2 + hstepB, voffB); PG8_STAGE(PG8_SA(0, 0), a2, voffA);
;             PG8_WAIT_V(8); PG8_WAIT_L(0); PG8_BAR; PG8_MMA(1, 0, At, B0); PG8_MMA(1, 1, At, B1); PG8_BAR; PG8_SCHED;
.LBB0_733:
	ds_read_b128 v[140:143], v149
	ds_read_b128 v[158:161], v149 offset:1024
	ds_read_b128 v[162:165], v149 offset:2048
	ds_read_b128 v[166:169], v149 offset:3072
	ds_read_b128 v[170:173], v150
	ds_read_b128 v[174:177], v150 offset:1024
	ds_read_b128 v[178:181], v150 offset:2048
	ds_read_b128 v[182:185], v150 offset:3072
	s_add_u32 s30, s28, 0xfff80080
	s_addc_u32 s31, s29, -1
	s_cmp_eq_u32 s56, 28
	s_cselect_b32 s35, s3, s31
	s_cselect_b32 s34, s21, s30
	s_cselect_b32 s31, s19, s55
	s_cselect_b32 s30, s51, s54
	v_lshl_add_u64 v[144:145], s[28:29], 0, v[132:133]
	s_add_i32 m0, s27, 0xc000
	ds_read_b128 v[186:189], v151
	ds_read_b128 v[190:193], v151 offset:1024
	ds_read_b128 v[194:197], v151 offset:2048
	ds_read_b128 v[198:201], v151 offset:3072
	ds_read_b128 v[202:205], v151 offset:4096
	ds_read_b128 v[206:209], v151 offset:5120
	ds_read_b128 v[210:213], v151 offset:6144
	ds_read_b128 v[214:217], v151 offset:7168
	global_load_lds_dwordx4 v[144:145], off
	v_lshl_add_u64 v[144:145], s[28:29], 0, v[134:135]
	s_add_i32 m0, s27, 0xe000
	s_nop 0
	global_load_lds_dwordx4 v[144:145], off
	s_waitcnt vmcnt(8)
	s_waitcnt lgkmcnt(0)
	s_barrier
	s_setprio 1
	s_waitcnt lgkmcnt(0)
	v_mfma_f32_16x16x32_bf16 v[124:127], v[140:143], v[186:189], v[124:127]
	v_mfma_f32_16x16x32_bf16 v[120:123], v[162:165], v[186:189], v[120:123]
	v_mfma_f32_16x16x32_bf16 v[108:111], v[140:143], v[194:197], v[108:111]
	v_mfma_f32_16x16x32_bf16 v[104:107], v[162:165], v[194:197], v[104:107]
	v_mfma_f32_16x16x32_bf16 v[92:95], v[140:143], v[202:205], v[92:95]
	v_mfma_f32_16x16x32_bf16 v[88:91], v[162:165], v[202:205], v[88:91]
	v_mfma_f32_16x16x32_bf16 v[76:79], v[140:143], v[210:213], v[76:79]
	v_mfma_f32_16x16x32_bf16 v[72:75], v[162:165], v[210:213], v[72:75]
	v_mfma_f32_16x16x32_bf16 v[124:127], v[158:161], v[190:193], v[124:127]
	v_mfma_f32_16x16x32_bf16 v[120:123], v[166:169], v[190:193], v[120:123]
	v_mfma_f32_16x16x32_bf16 v[108:111], v[158:161], v[198:201], v[108:111]
	v_mfma_f32_16x16x32_bf16 v[104:107], v[166:169], v[198:201], v[104:107]
	v_mfma_f32_16x16x32_bf16 v[92:95], v[158:161], v[206:209], v[92:95]
	v_mfma_f32_16x16x32_bf16 v[88:91], v[166:169], v[206:209], v[88:91]
	v_mfma_f32_16x16x32_bf16 v[76:79], v[158:161], v[214:217], v[76:79]
	v_mfma_f32_16x16x32_bf16 v[72:75], v[166:169], v[214:217], v[72:75]
	v_mfma_f32_16x16x32_bf16 v[116:119], v[170:173], v[186:189], v[116:119]
	v_mfma_f32_16x16x32_bf16 v[112:115], v[178:181], v[186:189], v[112:115]
	v_mfma_f32_16x16x32_bf16 v[100:103], v[170:173], v[194:197], v[100:103]
	v_mfma_f32_16x16x32_bf16 v[96:99], v[178:181], v[194:197], v[96:99]
	v_mfma_f32_16x16x32_bf16 v[84:87], v[170:173], v[202:205], v[84:87]
	v_mfma_f32_16x16x32_bf16 v[80:83], v[178:181], v[202:205], v[80:83]
	v_mfma_f32_16x16x32_bf16 v[68:71], v[170:173], v[210:213], v[68:71]
	v_mfma_f32_16x16x32_bf16 v[64:67], v[178:181], v[210:213], v[64:67]
	v_mfma_f32_16x16x32_bf16 v[116:119], v[174:177], v[190:193], v[116:119]
	v_mfma_f32_16x16x32_bf16 v[112:115], v[182:185], v[190:193], v[112:115]
	v_mfma_f32_16x16x32_bf16 v[100:103], v[174:177], v[198:201], v[100:103]
	v_mfma_f32_16x16x32_bf16 v[96:99], v[182:185], v[198:201], v[96:99]
	v_mfma_f32_16x16x32_bf16 v[84:87], v[174:177], v[206:209], v[84:87]
	v_mfma_f32_16x16x32_bf16 v[80:83], v[182:185], v[206:209], v[80:83]
	v_mfma_f32_16x16x32_bf16 v[68:71], v[174:177], v[214:217], v[68:71]
	v_mfma_f32_16x16x32_bf16 v[64:67], v[182:185], v[214:217], v[64:67]
	s_setprio 0
	s_barrier
	s_add_i32 s57, s49, s40
	v_lshl_add_u64 v[144:145], s[30:31], 0, v[128:129]
	s_mov_b32 m0, s57
	ds_read_b128 v[186:189], v151 offset:16384
	ds_read_b128 v[190:193], v151 offset:17408
	ds_read_b128 v[194:197], v151 offset:18432
	ds_read_b128 v[198:201], v151 offset:19456
	ds_read_b128 v[202:205], v151 offset:20480
	ds_read_b128 v[206:209], v151 offset:21504
	ds_read_b128 v[210:213], v151 offset:22528
	ds_read_b128 v[214:217], v151 offset:23552
	global_load_lds_dwordx4 v[144:145], off
	s_add_i32 m0, s57, 0x2000
	s_add_u32 s58, s30, 0x80000
	v_lshl_add_u64 v[154:155], s[30:31], 0, v[130:131]
	s_addc_u32 s59, s31, 0
	s_add_i32 s57, s50, s40
	global_load_lds_dwordx4 v[154:155], off
	v_lshl_add_u64 v[218:219], s[58:59], 0, v[128:129]
	s_mov_b32 m0, s57
	v_lshl_add_u64 v[220:221], s[34:35], 0, v[130:131]
	global_load_lds_dwordx4 v[218:219], off
	v_lshl_add_u64 v[218:219], s[58:59], 0, v[130:131]
	s_add_i32 m0, s57, 0x2000
	s_nop 0
	global_load_lds_dwordx4 v[218:219], off
	v_lshl_add_u64 v[218:219], s[34:35], 0, v[128:129]
	s_mov_b32 m0, s27
	s_nop 0
	global_load_lds_dwordx4 v[218:219], off
	s_mov_b32 m0, s41
	s_nop 0
	global_load_lds_dwordx4 v[220:221], off
	s_waitcnt vmcnt(8)
	s_waitcnt lgkmcnt(0)
	s_barrier
; #define PG8_STAGE(bufoff, gbase, voff) do { _Pragma("unroll") for (int _i = 0; _i < 2; ++_i) \
;         __builtin_amdgcn_global_load_lds((const unsigned*)((const char*)(gbase) + (voff)[_i]), (PG8_LAS unsigned*)(lds + (bufoff) + ldsw + _i * 8192), 16, 0, 0); } while (0)
; #define PG8_LDA(dst, b, h) do { _Pragma("unroll") for (int m = 0; m < 4; ++m) _Pragma("unroll") for (int k = 0; k < 2; ++k) dst[m][k] = *(const PG8_LAS bf16x8*)(lds + PG8_SA(b, h) + aoff + m * 2048 + k * 1024); } while (0)
; #define PG8_LDB(dst, b, h) do { _Pragma("unroll") for (int n = 0; n < 2; ++n) _Pragma("unroll") for (int k = 0; k < 2; ++k) dst[n][k] = *(const PG8_LAS bf16x8*)(lds + PG8_SB(b, h) + boff + n * 2048 + k * 1024); } while (0)
; #define PG8_MMA(ai, bj, At, Bt) do { __builtin_amdgcn_s_setprio(1); _Pragma("unroll") for (int m = 0; m < 4; ++m) _Pragma("unroll") for (int n = 0; n < 2; ++n) _Pragma("unroll") for (int k = 0; k < 2; ++k) \
;         acc[ai][bj][m][n] = __builtin_amdgcn_mfma_f32_16x16x32_bf16(Bt[n][k], At[m][k], acc[ai][bj][m][n], 0, 0, 0); __builtin_amdgcn_s_setprio(0); } while (0)
; #define PG8_WAIT_V(n) asm volatile("s_waitcnt vmcnt(" #n ")" ::: "memory")
; #define PG8_WAIT_L(n) asm volatile("s_waitcnt lgkmcnt(" #n ")" ::: "memory")
; #define PG8_BAR __builtin_amdgcn_s_barrier()
; #define PG8_SCHED __builtin_amdgcn_sched_barrier(0)
; template <class Epi, class Sched, bool ALIGN_EPI = false, bool SP2 = false>
; __device__ __forceinline__ void gemm_phase(PG8_LAS unsigned char* lds, const Gemm g, const Sched& S, const Epi& E) {
;     ...
;             PG8_WAIT_V(8); PG8_WAIT_L(0); PG8_BAR; PG8_MMA(1, 0, At, B0); PG8_MMA(1, 1, At, B1); PG8_BAR; PG8_SCHED;
;             PG8_LDB(B0, 1, 0); PG8_LDB(B1, 1, 1); PG8_SCHED; PG8_LDA(At, 1, 0); PG8_STAGE(PG8_SA(0, 1), a2 + hstepA, voffA);
;             PG8_WAIT_V(8); PG8_WAIT_L(0); PG8_BAR; PG8_MMA(0, 0, At, B0); PG8_MMA(0, 1, At, B1); PG8_BAR; PG8_SCHED;
	s_setprio 1
	s_waitcnt lgkmcnt(0)
	v_mfma_f32_16x16x32_bf16 v[60:63], v[140:143], v[186:189], v[60:63]
	v_mfma_f32_16x16x32_bf16 v[56:59], v[162:165], v[186:189], v[56:59]
	v_mfma_f32_16x16x32_bf16 v[44:47], v[140:143], v[194:197], v[44:47]
	v_mfma_f32_16x16x32_bf16 v[40:43], v[162:165], v[194:197], v[40:43]
	v_mfma_f32_16x16x32_bf16 v[28:31], v[140:143], v[202:205], v[28:31]
	v_mfma_f32_16x16x32_bf16 v[24:27], v[162:165], v[202:205], v[24:27]
	v_mfma_f32_16x16x32_bf16 v[12:15], v[140:143], v[210:213], v[12:15]
	v_mfma_f32_16x16x32_bf16 v[8:11], v[162:165], v[210:213], v[8:11]
	v_mfma_f32_16x16x32_bf16 v[60:63], v[158:161], v[190:193], v[60:63]
	v_mfma_f32_16x16x32_bf16 v[56:59], v[166:169], v[190:193], v[56:59]
	v_mfma_f32_16x16x32_bf16 v[44:47], v[158:161], v[198:201], v[44:47]
	v_mfma_f32_16x16x32_bf16 v[40:43], v[166:169], v[198:201], v[40:43]
	v_mfma_f32_16x16x32_bf16 v[28:31], v[158:161], v[206:209], v[28:31]
	v_mfma_f32_16x16x32_bf16 v[24:27], v[166:169], v[206:209], v[24:27]
	v_mfma_f32_16x16x32_bf16 v[12:15], v[158:161], v[214:217], v[12:15]
	v_mfma_f32_16x16x32_bf16 v[8:11], v[166:169], v[214:217], v[8:11]
	v_mfma_f32_16x16x32_bf16 v[52:55], v[170:173], v[186:189], v[52:55]
	v_mfma_f32_16x16x32_bf16 v[48:51], v[178:181], v[186:189], v[48:51]
	v_mfma_f32_16x16x32_bf16 v[36:39], v[170:173], v[194:197], v[36:39]
	v_mfma_f32_16x16x32_bf16 v[32:35], v[178:181], v[194:197], v[32:35]
	v_mfma_f32_16x16x32_bf16 v[20:23], v[170:173], v[202:205], v[20:23]
	v_mfma_f32_16x16x32_bf16 v[16:19], v[178:181], v[202:205], v[16:19]
	v_mfma_f32_16x16x32_bf16 v[4:7], v[170:173], v[210:213], v[4:7]
	v_mfma_f32_16x16x32_bf16 v[0:3], v[178:181], v[210:213], v[0:3]
	v_mfma_f32_16x16x32_bf16 v[52:55], v[174:177], v[190:193], v[52:55]
	v_mfma_f32_16x16x32_bf16 v[48:51], v[182:185], v[190:193], v[48:51]
	v_mfma_f32_16x16x32_bf16 v[36:39], v[174:177], v[198:201], v[36:39]
	v_mfma_f32_16x16x32_bf16 v[32:35], v[182:185], v[198:201], v[32:35]
	v_mfma_f32_16x16x32_bf16 v[20:23], v[174:177], v[206:209], v[20:23]
	v_mfma_f32_16x16x32_bf16 v[16:19], v[182:185], v[206:209], v[16:19]
	v_mfma_f32_16x16x32_bf16 v[4:7], v[174:177], v[214:217], v[4:7]
	v_mfma_f32_16x16x32_bf16 v[0:3], v[182:185], v[214:217], v[0:3]
	s_setprio 0
	s_barrier
	s_add_i32 s57, 0, 0x18000
	v_add_u32_e32 v153, s57, v147
	s_add_i32 s58, 0, 0x1c000
	ds_read_b128 v[140:143], v153
	ds_read_b128 v[158:161], v153 offset:1024
	ds_read_b128 v[162:165], v153 offset:2048
	ds_read_b128 v[166:169], v153 offset:3072
	v_add_u32_e32 v153, s58, v147
	ds_read_b128 v[170:173], v153
	ds_read_b128 v[174:177], v153 offset:1024
	ds_read_b128 v[178:181], v153 offset:2048
	ds_read_b128 v[182:185], v153 offset:3072
	s_add_u32 s34, s34, 0x80000
	s_addc_u32 s35, s35, 0
	s_mov_b32 m0, s42
	v_lshl_add_u64 v[222:223], s[34:35], 0, v[128:129]
	ds_read_b128 v[186:189], v151 offset:32768
	ds_read_b128 v[190:193], v151 offset:33792
	ds_read_b128 v[194:197], v151 offset:34816
	ds_read_b128 v[198:201], v151 offset:35840
	ds_read_b128 v[202:205], v151 offset:36864
	ds_read_b128 v[206:209], v151 offset:37888
	ds_read_b128 v[210:213], v151 offset:38912
	ds_read_b128 v[214:217], v151 offset:39936
	global_load_lds_dwordx4 v[222:223], off
	v_lshl_add_u64 v[222:223], s[34:35], 0, v[130:131]
	s_mov_b32 m0, s43
	s_nop 0
	global_load_lds_dwordx4 v[222:223], off
	s_waitcnt vmcnt(8)
	s_waitcnt lgkmcnt(0)
	s_barrier
	s_setprio 1
	s_waitcnt lgkmcnt(0)
	v_mfma_f32_16x16x32_bf16 v[124:127], v[140:143], v[186:189], v[124:127]
	v_mfma_f32_16x16x32_bf16 v[120:123], v[162:165], v[186:189], v[120:123]
	v_mfma_f32_16x16x32_bf16 v[108:111], v[140:143], v[194:197], v[108:111]
	v_mfma_f32_16x16x32_bf16 v[104:107], v[162:165], v[194:197], v[104:107]
	v_mfma_f32_16x16x32_bf16 v[92:95], v[140:143], v[202:205], v[92:95]
	v_mfma_f32_16x16x32_bf16 v[88:91], v[162:165], v[202:205], v[88:91]
	v_mfma_f32_16x16x32_bf16 v[76:79], v[140:143], v[210:213], v[76:79]
	v_mfma_f32_16x16x32_bf16 v[72:75], v[162:165], v[210:213], v[72:75]
	v_mfma_f32_16x16x32_bf16 v[124:127], v[158:161], v[190:193], v[124:127]
	v_mfma_f32_16x16x32_bf16 v[120:123], v[166:169], v[190:193], v[120:123]
	v_mfma_f32_16x16x32_bf16 v[108:111], v[158:161], v[198:201], v[108:111]
	v_mfma_f32_16x16x32_bf16 v[104:107], v[166:169], v[198:201], v[104:107]
	v_mfma_f32_16x16x32_bf16 v[92:95], v[158:161], v[206:209], v[92:95]
	v_mfma_f32_16x16x32_bf16 v[88:91], v[166:169], v[206:209], v[88:91]
	v_mfma_f32_16x16x32_bf16 v[76:79], v[158:161], v[214:217], v[76:79]
	v_mfma_f32_16x16x32_bf16 v[72:75], v[166:169], v[214:217], v[72:75]
	v_mfma_f32_16x16x32_bf16 v[116:119], v[170:173], v[186:189], v[116:119]
	v_mfma_f32_16x16x32_bf16 v[112:115], v[178:181], v[186:189], v[112:115]
	v_mfma_f32_16x16x32_bf16 v[100:103], v[170:173], v[194:197], v[100:103]
	v_mfma_f32_16x16x32_bf16 v[96:99], v[178:181], v[194:197], v[96:99]
	v_mfma_f32_16x16x32_bf16 v[84:87], v[170:173], v[202:205], v[84:87]
	v_mfma_f32_16x16x32_bf16 v[80:83], v[178:181], v[202:205], v[80:83]
	v_mfma_f32_16x16x32_bf16 v[68:71], v[170:173], v[210:213], v[68:71]
	v_mfma_f32_16x16x32_bf16 v[64:67], v[178:181], v[210:213], v[64:67]
	v_mfma_f32_16x16x32_bf16 v[116:119], v[174:177], v[190:193], v[116:119]
	v_mfma_f32_16x16x32_bf16 v[112:115], v[182:185], v[190:193], v[112:115]
	v_mfma_f32_16x16x32_bf16 v[100:103], v[174:177], v[198:201], v[100:103]
	v_mfma_f32_16x16x32_bf16 v[96:99], v[182:185], v[198:201], v[96:99]
	v_mfma_f32_16x16x32_bf16 v[84:87], v[174:177], v[206:209], v[84:87]
	v_mfma_f32_16x16x32_bf16 v[80:83], v[182:185], v[206:209], v[80:83]
	v_mfma_f32_16x16x32_bf16 v[68:71], v[174:177], v[214:217], v[68:71]
	v_mfma_f32_16x16x32_bf16 v[64:67], v[182:185], v[214:217], v[64:67]
	s_setprio 0
	s_barrier
; #define PG8_STAGE(bufoff, gbase, voff) do { _Pragma("unroll") for (int _i = 0; _i < 2; ++_i) \
;         __builtin_amdgcn_global_load_lds((const unsigned*)((const char*)(gbase) + (voff)[_i]), (PG8_LAS unsigned*)(lds + (bufoff) + ldsw + _i * 8192), 16, 0, 0); } while (0)
; #define PG8_LDA(dst, b, h) do { _Pragma("unroll") for (int m = 0; m < 4; ++m) _Pragma("unroll") for (int k = 0; k < 2; ++k) dst[m][k] = *(const PG8_LAS bf16x8*)(lds + PG8_SA(b, h) + aoff + m * 2048 + k * 1024); } while (0)
; #define PG8_MMA(ai, bj, At, Bt) do { __builtin_amdgcn_s_setprio(1); _Pragma("unroll") for (int m = 0; m < 4; ++m) _Pragma("unroll") for (int n = 0; n < 2; ++n) _Pragma("unroll") for (int k = 0; k < 2; ++k) \
;         acc[ai][bj][m][n] = __builtin_amdgcn_mfma_f32_16x16x32_bf16(Bt[n][k], At[m][k], acc[ai][bj][m][n], 0, 0, 0); __builtin_amdgcn_s_setprio(0); } while (0)
; #define PG8_WAIT_V(n) asm volatile("s_waitcnt vmcnt(" #n ")" ::: "memory")
; #define PG8_WAIT_L(n) asm volatile("s_waitcnt lgkmcnt(" #n ")" ::: "memory")
; #define PG8_BAR __builtin_amdgcn_s_barrier()
; #define PG8_SCHED __builtin_amdgcn_sched_barrier(0)
; template <class Epi, class Sched, bool ALIGN_EPI = false, bool SP2 = false>
; __device__ __forceinline__ void gemm_phase(PG8_LAS unsigned char* lds, const Gemm g, const Sched& S, const Epi& E) {
;     ...
;         for (int t = 0; t < nt; t += 2) {
;     ...
;             PG8_LDA(At, 1, 1); PG8_STAGE(PG8_SB(1, 0), b3, voffB); PG8_STAGE(PG8_SB(1, 1), b3 + hstepB, voffB); PG8_STAGE(PG8_SA(1, 0), a3, voffA);
;             PG8_WAIT_V(8); PG8_WAIT_L(0); PG8_BAR; PG8_MMA(1, 0, At, B0); PG8_MMA(1, 1, At, B1); PG8_BAR; PG8_SCHED;
	s_add_i32 s34, s57, s40
	v_lshl_add_u64 v[144:145], v[144:145], 0, s[14:15]
	s_mov_b32 m0, s34
	ds_read_b128 v[186:189], v151 offset:49152
	ds_read_b128 v[190:193], v151 offset:50176
	ds_read_b128 v[194:197], v151 offset:51200
	ds_read_b128 v[198:201], v151 offset:52224
	ds_read_b128 v[202:205], v151 offset:53248
	ds_read_b128 v[206:209], v151 offset:54272
	ds_read_b128 v[210:213], v151 offset:55296
	ds_read_b128 v[214:217], v151 offset:56320
	global_load_lds_dwordx4 v[144:145], off
	s_add_i32 m0, s34, 0x2000
	s_add_u32 s30, s30, 0x80080
	v_lshl_add_u64 v[144:145], v[154:155], 0, s[14:15]
	s_addc_u32 s31, s31, 0
	s_add_i32 s34, s58, s40
	global_load_lds_dwordx4 v[144:145], off
	v_lshl_add_u64 v[144:145], s[30:31], 0, v[128:129]
	s_mov_b32 m0, s34
	s_nop 0
	global_load_lds_dwordx4 v[144:145], off
	v_lshl_add_u64 v[144:145], s[30:31], 0, v[130:131]
	s_add_i32 m0, s34, 0x2000
	s_nop 0
	global_load_lds_dwordx4 v[144:145], off
	v_lshl_add_u64 v[144:145], v[218:219], 0, s[14:15]
	s_mov_b32 m0, s45
	s_nop 0
	global_load_lds_dwordx4 v[144:145], off
	v_lshl_add_u64 v[144:145], v[220:221], 0, s[14:15]
	s_mov_b32 m0, s46
	s_nop 0
	global_load_lds_dwordx4 v[144:145], off
	s_waitcnt vmcnt(8)
	s_waitcnt lgkmcnt(0)
	s_barrier
	s_setprio 1
	s_waitcnt lgkmcnt(0)
	v_mfma_f32_16x16x32_bf16 v[60:63], v[140:143], v[186:189], v[60:63]
	v_mfma_f32_16x16x32_bf16 v[56:59], v[162:165], v[186:189], v[56:59]
	v_mfma_f32_16x16x32_bf16 v[44:47], v[140:143], v[194:197], v[44:47]
	v_mfma_f32_16x16x32_bf16 v[40:43], v[162:165], v[194:197], v[40:43]
	v_mfma_f32_16x16x32_bf16 v[28:31], v[140:143], v[202:205], v[28:31]
	v_mfma_f32_16x16x32_bf16 v[24:27], v[162:165], v[202:205], v[24:27]
	v_mfma_f32_16x16x32_bf16 v[12:15], v[140:143], v[210:213], v[12:15]
	v_mfma_f32_16x16x32_bf16 v[8:11], v[162:165], v[210:213], v[8:11]
	v_mfma_f32_16x16x32_bf16 v[60:63], v[158:161], v[190:193], v[60:63]
	v_mfma_f32_16x16x32_bf16 v[56:59], v[166:169], v[190:193], v[56:59]
	v_mfma_f32_16x16x32_bf16 v[44:47], v[158:161], v[198:201], v[44:47]
	v_mfma_f32_16x16x32_bf16 v[40:43], v[166:169], v[198:201], v[40:43]
	v_mfma_f32_16x16x32_bf16 v[28:31], v[158:161], v[206:209], v[28:31]
	v_mfma_f32_16x16x32_bf16 v[24:27], v[166:169], v[206:209], v[24:27]
	v_mfma_f32_16x16x32_bf16 v[12:15], v[158:161], v[214:217], v[12:15]
	v_mfma_f32_16x16x32_bf16 v[8:11], v[166:169], v[214:217], v[8:11]
	v_mfma_f32_16x16x32_bf16 v[52:55], v[170:173], v[186:189], v[52:55]
	v_mfma_f32_16x16x32_bf16 v[48:51], v[178:181], v[186:189], v[48:51]
	v_mfma_f32_16x16x32_bf16 v[36:39], v[170:173], v[194:197], v[36:39]
	v_mfma_f32_16x16x32_bf16 v[32:35], v[178:181], v[194:197], v[32:35]
	v_mfma_f32_16x16x32_bf16 v[20:23], v[170:173], v[202:205], v[20:23]
	v_mfma_f32_16x16x32_bf16 v[16:19], v[178:181], v[202:205], v[16:19]
	v_mfma_f32_16x16x32_bf16 v[4:7], v[170:173], v[210:213], v[4:7]
	v_mfma_f32_16x16x32_bf16 v[0:3], v[178:181], v[210:213], v[0:3]
	v_mfma_f32_16x16x32_bf16 v[52:55], v[174:177], v[190:193], v[52:55]
	v_mfma_f32_16x16x32_bf16 v[48:51], v[182:185], v[190:193], v[48:51]
	v_mfma_f32_16x16x32_bf16 v[36:39], v[174:177], v[198:201], v[36:39]
	v_mfma_f32_16x16x32_bf16 v[32:35], v[182:185], v[198:201], v[32:35]
	v_mfma_f32_16x16x32_bf16 v[20:23], v[174:177], v[206:209], v[20:23]
	v_mfma_f32_16x16x32_bf16 v[16:19], v[182:185], v[206:209], v[16:19]
	v_mfma_f32_16x16x32_bf16 v[4:7], v[174:177], v[214:217], v[4:7]
	v_mfma_f32_16x16x32_bf16 v[0:3], v[182:185], v[214:217], v[0:3]
	s_add_i32 s56, s56, 2
	s_add_u32 s28, s28, 0x100
	s_addc_u32 s29, s29, 0
	s_add_u32 s54, s54, 0x100
	s_addc_u32 s55, s55, 0
	s_cmp_gt_u32 s56, 29
	s_setprio 0
	s_barrier
	s_cbranch_scc0 .LBB0_733
	s_and_b64 vcc, exec, s[16:17]
	s_cbranch_vccz .LBB0_736
	s_barrier

; #define PG8_STAGE(bufoff, gbase, voff) do { _Pragma("unroll") for (int _i = 0; _i < 2; ++_i) \
;         __builtin_amdgcn_global_load_lds((const unsigned*)((const char*)(gbase) + (voff)[_i]), (PG8_LAS unsigned*)(lds + (bufoff) + ldsw + _i * 8192), 16, 0, 0); } while (0)
; #define PG8_LDA(dst, b, h) do { _Pragma("unroll") for (int m = 0; m < 4; ++m) _Pragma("unroll") for (int k = 0; k < 2; ++k) dst[m][k] = *(const PG8_LAS bf16x8*)(lds + PG8_SA(b, h) + aoff + m * 2048 + k * 1024); } while (0)
; #define PG8_LDB(dst, b, h) do { _Pragma("unroll") for (int n = 0; n < 2; ++n) _Pragma("unroll") for (int k = 0; k < 2; ++k) dst[n][k] = *(const PG8_LAS bf16x8*)(lds + PG8_SB(b, h) + boff + n * 2048 + k * 1024); } while (0)
; #define PG8_MMA(ai, bj, At, Bt) do { __builtin_amdgcn_s_setprio(1); _Pragma("unroll") for (int m = 0; m < 4; ++m) _Pragma("unroll") for (int n = 0; n < 2; ++n) _Pragma("unroll") for (int k = 0; k < 2; ++k) \
;         acc[ai][bj][m][n] = __builtin_amdgcn_mfma_f32_16x16x32_bf16(Bt[n][k], At[m][k], acc[ai][bj][m][n], 0, 0, 0); __builtin_amdgcn_s_setprio(0); } while (0)
; #define PG8_WAIT_V(n) asm volatile("s_waitcnt vmcnt(" #n ")" ::: "memory")
; #define PG8_WAIT_L(n) asm volatile("s_waitcnt lgkmcnt(" #n ")" ::: "memory")
; template <class Epi, class Sched, bool ALIGN_EPI = false, bool SP2 = false>
; __device__ __forceinline__ void gemm_phase(PG8_LAS unsigned char* lds, const Gemm g, const Sched& S, const Epi& E) {
;     ...
;             const bool last = (t == nt - 2);
;             const char* a1 = cA + (size_t)(t + 1) * kstep;
;             const char* a2 = last ? nA : cA + (size_t)(t + 2) * kstep; const char* b2 = last ? nB : cB + (size_t)(t + 2) * kstep;
;             const char* a3 = a2 + kstep; const char* b3 = b2 + kstep;
;             if (last && has_next) S.a_ready(nxt);
;             if constexpr (SP2) {
;             PG8_LDB(B0, 0, 0); PG8_LDB(B1, 0, 1); PG8_SCHED; PG8_LDA(At, 0, 0); PG8_STAGE(PG8_SA(1, 1), a1 + hstepA, voffA);
;             PG8_WAIT_V(8); PG8_WAIT_L(0); PG8_BAR; PG8_MMA(0, 0, At, B0); PG8_MMA(0, 1, At, B1); PG8_BAR; PG8_SCHED;
;             PG8_LDA(At, 0, 1); PG8_STAGE(PG8_SB(0, 0), b2, voffB); PG8_STAGE(PG8_SB(0, 1), b2 + hstepB, voffB); PG8_STAGE(PG8_SA(0, 0), a2, voffA);
;             PG8_WAIT_V(8); PG8_WAIT_L(0); PG8_BAR; PG8_MMA(1, 0, At, B0); PG8_MMA(1, 1, At, B1); PG8_BAR; PG8_SCHED;
.LBB0_824:
	ds_read_b128 v[144:147], v155
	ds_read_b128 v[148:151], v155 offset:1024
	ds_read_b128 v[162:165], v155 offset:2048
	ds_read_b128 v[166:169], v155 offset:3072
	ds_read_b128 v[170:173], v158
	ds_read_b128 v[174:177], v158 offset:1024
	ds_read_b128 v[178:181], v158 offset:2048
	ds_read_b128 v[182:185], v158 offset:3072
	s_add_u32 s36, s4, 0xfff80080
	s_addc_u32 s37, s5, -1
	s_cmp_eq_u32 s65, 28
	s_cselect_b32 s39, s29, s37
	s_cselect_b32 s38, s61, s36
	s_cselect_b32 s37, s27, s64
	s_cselect_b32 s36, s62, s63
	v_lshl_add_u64 v[218:219], s[4:5], 0, v[136:137]
	s_add_i32 m0, s3, 0xc000
	ds_read_b128 v[186:189], v159
	ds_read_b128 v[190:193], v159 offset:1024
	ds_read_b128 v[194:197], v159 offset:2048
	ds_read_b128 v[198:201], v159 offset:3072
	ds_read_b128 v[202:205], v159 offset:4096
	ds_read_b128 v[206:209], v159 offset:5120
	ds_read_b128 v[210:213], v159 offset:6144
	ds_read_b128 v[214:217], v159 offset:7168
	global_load_lds_dwordx4 v[218:219], off
	v_lshl_add_u64 v[218:219], s[4:5], 0, v[138:139]
	s_add_i32 m0, s3, 0xe000
	s_nop 0
	global_load_lds_dwordx4 v[218:219], off
	s_waitcnt vmcnt(8)
	s_waitcnt lgkmcnt(0)
	s_barrier
	s_setprio 1
	s_waitcnt lgkmcnt(0)
	v_mfma_f32_16x16x32_bf16 v[124:127], v[144:147], v[186:189], v[124:127]
	v_mfma_f32_16x16x32_bf16 v[120:123], v[162:165], v[186:189], v[120:123]
	v_mfma_f32_16x16x32_bf16 v[108:111], v[144:147], v[194:197], v[108:111]
	v_mfma_f32_16x16x32_bf16 v[104:107], v[162:165], v[194:197], v[104:107]
	v_mfma_f32_16x16x32_bf16 v[92:95], v[144:147], v[202:205], v[92:95]
	v_mfma_f32_16x16x32_bf16 v[88:91], v[162:165], v[202:205], v[88:91]
	v_mfma_f32_16x16x32_bf16 v[76:79], v[144:147], v[210:213], v[76:79]
	v_mfma_f32_16x16x32_bf16 v[72:75], v[162:165], v[210:213], v[72:75]
	v_mfma_f32_16x16x32_bf16 v[124:127], v[148:151], v[190:193], v[124:127]
	v_mfma_f32_16x16x32_bf16 v[120:123], v[166:169], v[190:193], v[120:123]
	v_mfma_f32_16x16x32_bf16 v[108:111], v[148:151], v[198:201], v[108:111]
	v_mfma_f32_16x16x32_bf16 v[104:107], v[166:169], v[198:201], v[104:107]
	v_mfma_f32_16x16x32_bf16 v[92:95], v[148:151], v[206:209], v[92:95]
	v_mfma_f32_16x16x32_bf16 v[88:91], v[166:169], v[206:209], v[88:91]
	v_mfma_f32_16x16x32_bf16 v[76:79], v[148:151], v[214:217], v[76:79]
	v_mfma_f32_16x16x32_bf16 v[72:75], v[166:169], v[214:217], v[72:75]
	v_mfma_f32_16x16x32_bf16 v[116:119], v[170:173], v[186:189], v[116:119]
	v_mfma_f32_16x16x32_bf16 v[112:115], v[178:181], v[186:189], v[112:115]
	v_mfma_f32_16x16x32_bf16 v[100:103], v[170:173], v[194:197], v[100:103]
	v_mfma_f32_16x16x32_bf16 v[96:99], v[178:181], v[194:197], v[96:99]
	v_mfma_f32_16x16x32_bf16 v[84:87], v[170:173], v[202:205], v[84:87]
	v_mfma_f32_16x16x32_bf16 v[80:83], v[178:181], v[202:205], v[80:83]
	v_mfma_f32_16x16x32_bf16 v[68:71], v[170:173], v[210:213], v[68:71]
	v_mfma_f32_16x16x32_bf16 v[64:67], v[178:181], v[210:213], v[64:67]
	v_mfma_f32_16x16x32_bf16 v[116:119], v[174:177], v[190:193], v[116:119]
	v_mfma_f32_16x16x32_bf16 v[112:115], v[182:185], v[190:193], v[112:115]
	v_mfma_f32_16x16x32_bf16 v[100:103], v[174:177], v[198:201], v[100:103]
	v_mfma_f32_16x16x32_bf16 v[96:99], v[182:185], v[198:201], v[96:99]
	v_mfma_f32_16x16x32_bf16 v[84:87], v[174:177], v[206:209], v[84:87]
	v_mfma_f32_16x16x32_bf16 v[80:83], v[182:185], v[206:209], v[80:83]
	v_mfma_f32_16x16x32_bf16 v[68:71], v[174:177], v[214:217], v[68:71]
	v_mfma_f32_16x16x32_bf16 v[64:67], v[182:185], v[214:217], v[64:67]
	s_setprio 0
	s_barrier
	s_add_i32 s66, s53, s45
	v_lshl_add_u64 v[218:219], s[36:37], 0, v[130:131]
	s_mov_b32 m0, s66
	ds_read_b128 v[186:189], v159 offset:16384
	ds_read_b128 v[190:193], v159 offset:17408
	ds_read_b128 v[194:197], v159 offset:18432
	ds_read_b128 v[198:201], v159 offset:19456
	ds_read_b128 v[202:205], v159 offset:20480
	ds_read_b128 v[206:209], v159 offset:21504
	ds_read_b128 v[210:213], v159 offset:22528
	ds_read_b128 v[214:217], v159 offset:23552
	global_load_lds_dwordx4 v[218:219], off
	s_add_i32 m0, s66, 0x2000
	s_add_u32 s66, s36, 0x80000
	v_lshl_add_u64 v[220:221], s[36:37], 0, v[134:135]
	s_addc_u32 s67, s37, 0
	s_add_i32 s68, s54, s45
	global_load_lds_dwordx4 v[220:221], off
	v_lshl_add_u64 v[222:223], s[66:67], 0, v[130:131]
	s_mov_b32 m0, s68
	v_lshl_add_u64 v[224:225], s[38:39], 0, v[132:133]
	global_load_lds_dwordx4 v[222:223], off
	v_lshl_add_u64 v[222:223], s[66:67], 0, v[134:135]
	s_add_i32 m0, s68, 0x2000
	s_nop 0
	global_load_lds_dwordx4 v[222:223], off
	v_lshl_add_u64 v[222:223], s[38:39], 0, v[128:129]
	s_mov_b32 m0, s3
	s_nop 0
	global_load_lds_dwordx4 v[222:223], off
	s_mov_b32 m0, s46
	s_nop 0
	global_load_lds_dwordx4 v[224:225], off
	s_waitcnt vmcnt(8)
	s_waitcnt lgkmcnt(0)
	s_barrier
; #define PG8_STAGE(bufoff, gbase, voff) do { _Pragma("unroll") for (int _i = 0; _i < 2; ++_i) \
;         __builtin_amdgcn_global_load_lds((const unsigned*)((const char*)(gbase) + (voff)[_i]), (PG8_LAS unsigned*)(lds + (bufoff) + ldsw + _i * 8192), 16, 0, 0); } while (0)
; #define PG8_LDA(dst, b, h) do { _Pragma("unroll") for (int m = 0; m < 4; ++m) _Pragma("unroll") for (int k = 0; k < 2; ++k) dst[m][k] = *(const PG8_LAS bf16x8*)(lds + PG8_SA(b, h) + aoff + m * 2048 + k * 1024); } while (0)
; #define PG8_LDB(dst, b, h) do { _Pragma("unroll") for (int n = 0; n < 2; ++n) _Pragma("unroll") for (int k = 0; k < 2; ++k) dst[n][k] = *(const PG8_LAS bf16x8*)(lds + PG8_SB(b, h) + boff + n * 2048 + k * 1024); } while (0)
; #define PG8_MMA(ai, bj, At, Bt) do { __builtin_amdgcn_s_setprio(1); _Pragma("unroll") for (int m = 0; m < 4; ++m) _Pragma("unroll") for (int n = 0; n < 2; ++n) _Pragma("unroll") for (int k = 0; k < 2; ++k) \
;         acc[ai][bj][m][n] = __builtin_amdgcn_mfma_f32_16x16x32_bf16(Bt[n][k], At[m][k], acc[ai][bj][m][n], 0, 0, 0); __builtin_amdgcn_s_setprio(0); } while (0)
; #define PG8_WAIT_V(n) asm volatile("s_waitcnt vmcnt(" #n ")" ::: "memory")
; #define PG8_WAIT_L(n) asm volatile("s_waitcnt lgkmcnt(" #n ")" ::: "memory")
; #define PG8_BAR __builtin_amdgcn_s_barrier()
; #define PG8_SCHED __builtin_amdgcn_sched_barrier(0)
; template <class Epi, class Sched, bool ALIGN_EPI = false, bool SP2 = false>
; __device__ __forceinline__ void gemm_phase(PG8_LAS unsigned char* lds, const Gemm g, const Sched& S, const Epi& E) {
;     ...
;             PG8_WAIT_V(8); PG8_WAIT_L(0); PG8_BAR; PG8_MMA(1, 0, At, B0); PG8_MMA(1, 1, At, B1); PG8_BAR; PG8_SCHED;
;             PG8_LDB(B0, 1, 0); PG8_LDB(B1, 1, 1); PG8_SCHED; PG8_LDA(At, 1, 0); PG8_STAGE(PG8_SA(0, 1), a2 + hstepA, voffA);
;             PG8_WAIT_V(8); PG8_WAIT_L(0); PG8_BAR; PG8_MMA(0, 0, At, B0); PG8_MMA(0, 1, At, B1); PG8_BAR; PG8_SCHED;
	s_setprio 1
	s_waitcnt lgkmcnt(0)
	v_mfma_f32_16x16x32_bf16 v[60:63], v[144:147], v[186:189], v[60:63]
	v_mfma_f32_16x16x32_bf16 v[56:59], v[162:165], v[186:189], v[56:59]
	v_mfma_f32_16x16x32_bf16 v[44:47], v[144:147], v[194:197], v[44:47]
	v_mfma_f32_16x16x32_bf16 v[40:43], v[162:165], v[194:197], v[40:43]
	v_mfma_f32_16x16x32_bf16 v[28:31], v[144:147], v[202:205], v[28:31]
	v_mfma_f32_16x16x32_bf16 v[24:27], v[162:165], v[202:205], v[24:27]
	v_mfma_f32_16x16x32_bf16 v[12:15], v[144:147], v[210:213], v[12:15]
	v_mfma_f32_16x16x32_bf16 v[8:11], v[162:165], v[210:213], v[8:11]
	v_mfma_f32_16x16x32_bf16 v[60:63], v[148:151], v[190:193], v[60:63]
	v_mfma_f32_16x16x32_bf16 v[56:59], v[166:169], v[190:193], v[56:59]
	v_mfma_f32_16x16x32_bf16 v[44:47], v[148:151], v[198:201], v[44:47]
	v_mfma_f32_16x16x32_bf16 v[40:43], v[166:169], v[198:201], v[40:43]
	v_mfma_f32_16x16x32_bf16 v[28:31], v[148:151], v[206:209], v[28:31]
	v_mfma_f32_16x16x32_bf16 v[24:27], v[166:169], v[206:209], v[24:27]
	v_mfma_f32_16x16x32_bf16 v[12:15], v[148:151], v[214:217], v[12:15]
	v_mfma_f32_16x16x32_bf16 v[8:11], v[166:169], v[214:217], v[8:11]
	v_mfma_f32_16x16x32_bf16 v[52:55], v[170:173], v[186:189], v[52:55]
	v_mfma_f32_16x16x32_bf16 v[48:51], v[178:181], v[186:189], v[48:51]
	v_mfma_f32_16x16x32_bf16 v[36:39], v[170:173], v[194:197], v[36:39]
	v_mfma_f32_16x16x32_bf16 v[32:35], v[178:181], v[194:197], v[32:35]
	v_mfma_f32_16x16x32_bf16 v[20:23], v[170:173], v[202:205], v[20:23]
	v_mfma_f32_16x16x32_bf16 v[16:19], v[178:181], v[202:205], v[16:19]
	v_mfma_f32_16x16x32_bf16 v[4:7], v[170:173], v[210:213], v[4:7]
	v_mfma_f32_16x16x32_bf16 v[0:3], v[178:181], v[210:213], v[0:3]
	v_mfma_f32_16x16x32_bf16 v[52:55], v[174:177], v[190:193], v[52:55]
	v_mfma_f32_16x16x32_bf16 v[48:51], v[182:185], v[190:193], v[48:51]
	v_mfma_f32_16x16x32_bf16 v[36:39], v[174:177], v[198:201], v[36:39]
	v_mfma_f32_16x16x32_bf16 v[32:35], v[182:185], v[198:201], v[32:35]
	v_mfma_f32_16x16x32_bf16 v[20:23], v[174:177], v[206:209], v[20:23]
	v_mfma_f32_16x16x32_bf16 v[16:19], v[182:185], v[206:209], v[16:19]
	v_mfma_f32_16x16x32_bf16 v[4:7], v[174:177], v[214:217], v[4:7]
	v_mfma_f32_16x16x32_bf16 v[0:3], v[182:185], v[214:217], v[0:3]
	s_setprio 0
	s_barrier
	s_add_i32 s66, 0, 0x18000
	s_add_i32 s67, 0, 0x1c000
	v_add_u32_e32 v166, s66, v153
	v_add_u32_e32 v182, s67, v153
	ds_read_b128 v[144:147], v166
	ds_read_b128 v[148:151], v166 offset:1024
	ds_read_b128 v[162:165], v166 offset:2048
	ds_read_b128 v[166:169], v166 offset:3072
	ds_read_b128 v[170:173], v182
	ds_read_b128 v[174:177], v182 offset:1024
	ds_read_b128 v[178:181], v182 offset:2048
	ds_read_b128 v[182:185], v182 offset:3072
	s_add_u32 s38, s38, 0x80000
	s_addc_u32 s39, s39, 0
	s_mov_b32 m0, s47
	v_lshl_add_u64 v[226:227], s[38:39], 0, v[128:129]
	ds_read_b128 v[186:189], v159 offset:32768
	ds_read_b128 v[190:193], v159 offset:33792
	ds_read_b128 v[194:197], v159 offset:34816
	ds_read_b128 v[198:201], v159 offset:35840
	ds_read_b128 v[202:205], v159 offset:36864
	ds_read_b128 v[206:209], v159 offset:37888
	ds_read_b128 v[210:213], v159 offset:38912
	ds_read_b128 v[214:217], v159 offset:39936
	global_load_lds_dwordx4 v[226:227], off
	v_lshl_add_u64 v[226:227], s[38:39], 0, v[132:133]
	s_mov_b32 m0, s48
	s_nop 0
	global_load_lds_dwordx4 v[226:227], off
	s_waitcnt vmcnt(8)
	s_waitcnt lgkmcnt(0)
	s_barrier
	s_setprio 1
	s_waitcnt lgkmcnt(0)
	v_mfma_f32_16x16x32_bf16 v[124:127], v[144:147], v[186:189], v[124:127]
	v_mfma_f32_16x16x32_bf16 v[120:123], v[162:165], v[186:189], v[120:123]
	v_mfma_f32_16x16x32_bf16 v[108:111], v[144:147], v[194:197], v[108:111]
	v_mfma_f32_16x16x32_bf16 v[104:107], v[162:165], v[194:197], v[104:107]
	v_mfma_f32_16x16x32_bf16 v[92:95], v[144:147], v[202:205], v[92:95]
	v_mfma_f32_16x16x32_bf16 v[88:91], v[162:165], v[202:205], v[88:91]
	v_mfma_f32_16x16x32_bf16 v[76:79], v[144:147], v[210:213], v[76:79]
	v_mfma_f32_16x16x32_bf16 v[72:75], v[162:165], v[210:213], v[72:75]
	v_mfma_f32_16x16x32_bf16 v[124:127], v[148:151], v[190:193], v[124:127]
	v_mfma_f32_16x16x32_bf16 v[120:123], v[166:169], v[190:193], v[120:123]
	v_mfma_f32_16x16x32_bf16 v[108:111], v[148:151], v[198:201], v[108:111]
	v_mfma_f32_16x16x32_bf16 v[104:107], v[166:169], v[198:201], v[104:107]
	v_mfma_f32_16x16x32_bf16 v[92:95], v[148:151], v[206:209], v[92:95]
	v_mfma_f32_16x16x32_bf16 v[88:91], v[166:169], v[206:209], v[88:91]
	v_mfma_f32_16x16x32_bf16 v[76:79], v[148:151], v[214:217], v[76:79]
	v_mfma_f32_16x16x32_bf16 v[72:75], v[166:169], v[214:217], v[72:75]
	v_mfma_f32_16x16x32_bf16 v[116:119], v[170:173], v[186:189], v[116:119]
	v_mfma_f32_16x16x32_bf16 v[112:115], v[178:181], v[186:189], v[112:115]
	v_mfma_f32_16x16x32_bf16 v[100:103], v[170:173], v[194:197], v[100:103]
	v_mfma_f32_16x16x32_bf16 v[96:99], v[178:181], v[194:197], v[96:99]
	v_mfma_f32_16x16x32_bf16 v[84:87], v[170:173], v[202:205], v[84:87]
	v_mfma_f32_16x16x32_bf16 v[80:83], v[178:181], v[202:205], v[80:83]
	v_mfma_f32_16x16x32_bf16 v[68:71], v[170:173], v[210:213], v[68:71]
	v_mfma_f32_16x16x32_bf16 v[64:67], v[178:181], v[210:213], v[64:67]
	v_mfma_f32_16x16x32_bf16 v[116:119], v[174:177], v[190:193], v[116:119]
	v_mfma_f32_16x16x32_bf16 v[112:115], v[182:185], v[190:193], v[112:115]
	v_mfma_f32_16x16x32_bf16 v[100:103], v[174:177], v[198:201], v[100:103]
	v_mfma_f32_16x16x32_bf16 v[96:99], v[182:185], v[198:201], v[96:99]
	v_mfma_f32_16x16x32_bf16 v[84:87], v[174:177], v[206:209], v[84:87]
	v_mfma_f32_16x16x32_bf16 v[80:83], v[182:185], v[206:209], v[80:83]
	v_mfma_f32_16x16x32_bf16 v[68:71], v[174:177], v[214:217], v[68:71]
	v_mfma_f32_16x16x32_bf16 v[64:67], v[182:185], v[214:217], v[64:67]
	s_setprio 0
	s_barrier
; #define PG8_STAGE(bufoff, gbase, voff) do { _Pragma("unroll") for (int _i = 0; _i < 2; ++_i) \
;         __builtin_amdgcn_global_load_lds((const unsigned*)((const char*)(gbase) + (voff)[_i]), (PG8_LAS unsigned*)(lds + (bufoff) + ldsw + _i * 8192), 16, 0, 0); } while (0)
; #define PG8_LDA(dst, b, h) do { _Pragma("unroll") for (int m = 0; m < 4; ++m) _Pragma("unroll") for (int k = 0; k < 2; ++k) dst[m][k] = *(const PG8_LAS bf16x8*)(lds + PG8_SA(b, h) + aoff + m * 2048 + k * 1024); } while (0)
; #define PG8_MMA(ai, bj, At, Bt) do { __builtin_amdgcn_s_setprio(1); _Pragma("unroll") for (int m = 0; m < 4; ++m) _Pragma("unroll") for (int n = 0; n < 2; ++n) _Pragma("unroll") for (int k = 0; k < 2; ++k) \
;         acc[ai][bj][m][n] = __builtin_amdgcn_mfma_f32_16x16x32_bf16(Bt[n][k], At[m][k], acc[ai][bj][m][n], 0, 0, 0); __builtin_amdgcn_s_setprio(0); } while (0)
; #define PG8_WAIT_V(n) asm volatile("s_waitcnt vmcnt(" #n ")" ::: "memory")
; #define PG8_WAIT_L(n) asm volatile("s_waitcnt lgkmcnt(" #n ")" ::: "memory")
; #define PG8_BAR __builtin_amdgcn_s_barrier()
; #define PG8_SCHED __builtin_amdgcn_sched_barrier(0)
; template <class Epi, class Sched, bool ALIGN_EPI = false, bool SP2 = false>
; __device__ __forceinline__ void gemm_phase(PG8_LAS unsigned char* lds, const Gemm g, const Sched& S, const Epi& E) {
;     ...
;         for (int t = 0; t < nt; t += 2) {
;     ...
;             PG8_LDA(At, 1, 1); PG8_STAGE(PG8_SB(1, 0), b3, voffB); PG8_STAGE(PG8_SB(1, 1), b3 + hstepB, voffB); PG8_STAGE(PG8_SA(1, 0), a3, voffA);
;             PG8_WAIT_V(8); PG8_WAIT_L(0); PG8_BAR; PG8_MMA(1, 0, At, B0); PG8_MMA(1, 1, At, B1); PG8_BAR; PG8_SCHED;
	s_add_i32 s38, s66, s45
	v_lshl_add_u64 v[218:219], v[218:219], 0, s[14:15]
	s_mov_b32 m0, s38
	ds_read_b128 v[186:189], v159 offset:49152
	ds_read_b128 v[190:193], v159 offset:50176
	ds_read_b128 v[194:197], v159 offset:51200
	ds_read_b128 v[198:201], v159 offset:52224
	ds_read_b128 v[202:205], v159 offset:53248
	ds_read_b128 v[206:209], v159 offset:54272
	ds_read_b128 v[210:213], v159 offset:55296
	ds_read_b128 v[214:217], v159 offset:56320
	global_load_lds_dwordx4 v[218:219], off
	s_add_i32 m0, s38, 0x2000
	s_add_u32 s36, s36, 0x80080
	v_lshl_add_u64 v[218:219], v[220:221], 0, s[14:15]
	s_addc_u32 s37, s37, 0
	s_add_i32 s38, s67, s45
	global_load_lds_dwordx4 v[218:219], off
	v_lshl_add_u64 v[218:219], s[36:37], 0, v[130:131]
	s_mov_b32 m0, s38
	s_nop 0
	global_load_lds_dwordx4 v[218:219], off
	v_lshl_add_u64 v[218:219], s[36:37], 0, v[134:135]
	s_add_i32 m0, s38, 0x2000
	s_nop 0
	global_load_lds_dwordx4 v[218:219], off
	v_lshl_add_u64 v[218:219], v[222:223], 0, s[14:15]
	s_mov_b32 m0, s50
	s_nop 0
	global_load_lds_dwordx4 v[218:219], off
	v_lshl_add_u64 v[218:219], v[224:225], 0, s[14:15]
	s_mov_b32 m0, s51
	s_nop 0
	global_load_lds_dwordx4 v[218:219], off
	s_waitcnt vmcnt(8)
	s_waitcnt lgkmcnt(0)
	s_barrier
	s_setprio 1
	s_waitcnt lgkmcnt(0)
	v_mfma_f32_16x16x32_bf16 v[60:63], v[144:147], v[186:189], v[60:63]
	v_mfma_f32_16x16x32_bf16 v[56:59], v[162:165], v[186:189], v[56:59]
	v_mfma_f32_16x16x32_bf16 v[44:47], v[144:147], v[194:197], v[44:47]
	v_mfma_f32_16x16x32_bf16 v[40:43], v[162:165], v[194:197], v[40:43]
	v_mfma_f32_16x16x32_bf16 v[28:31], v[144:147], v[202:205], v[28:31]
	v_mfma_f32_16x16x32_bf16 v[24:27], v[162:165], v[202:205], v[24:27]
	v_mfma_f32_16x16x32_bf16 v[12:15], v[144:147], v[210:213], v[12:15]
	v_mfma_f32_16x16x32_bf16 v[8:11], v[162:165], v[210:213], v[8:11]
	v_mfma_f32_16x16x32_bf16 v[60:63], v[148:151], v[190:193], v[60:63]
	v_mfma_f32_16x16x32_bf16 v[56:59], v[166:169], v[190:193], v[56:59]
	v_mfma_f32_16x16x32_bf16 v[44:47], v[148:151], v[198:201], v[44:47]
	v_mfma_f32_16x16x32_bf16 v[40:43], v[166:169], v[198:201], v[40:43]
	v_mfma_f32_16x16x32_bf16 v[28:31], v[148:151], v[206:209], v[28:31]
	v_mfma_f32_16x16x32_bf16 v[24:27], v[166:169], v[206:209], v[24:27]
	v_mfma_f32_16x16x32_bf16 v[12:15], v[148:151], v[214:217], v[12:15]
	v_mfma_f32_16x16x32_bf16 v[8:11], v[166:169], v[214:217], v[8:11]
	v_mfma_f32_16x16x32_bf16 v[52:55], v[170:173], v[186:189], v[52:55]
	v_mfma_f32_16x16x32_bf16 v[48:51], v[178:181], v[186:189], v[48:51]
	v_mfma_f32_16x16x32_bf16 v[36:39], v[170:173], v[194:197], v[36:39]
	v_mfma_f32_16x16x32_bf16 v[32:35], v[178:181], v[194:197], v[32:35]
	v_mfma_f32_16x16x32_bf16 v[20:23], v[170:173], v[202:205], v[20:23]
	v_mfma_f32_16x16x32_bf16 v[16:19], v[178:181], v[202:205], v[16:19]
	v_mfma_f32_16x16x32_bf16 v[4:7], v[170:173], v[210:213], v[4:7]
	v_mfma_f32_16x16x32_bf16 v[0:3], v[178:181], v[210:213], v[0:3]
	v_mfma_f32_16x16x32_bf16 v[52:55], v[174:177], v[190:193], v[52:55]
	v_mfma_f32_16x16x32_bf16 v[48:51], v[182:185], v[190:193], v[48:51]
	v_mfma_f32_16x16x32_bf16 v[36:39], v[174:177], v[198:201], v[36:39]
	v_mfma_f32_16x16x32_bf16 v[32:35], v[182:185], v[198:201], v[32:35]
	v_mfma_f32_16x16x32_bf16 v[20:23], v[174:177], v[206:209], v[20:23]
	v_mfma_f32_16x16x32_bf16 v[16:19], v[182:185], v[206:209], v[16:19]
	v_mfma_f32_16x16x32_bf16 v[4:7], v[174:177], v[214:217], v[4:7]
	v_mfma_f32_16x16x32_bf16 v[0:3], v[182:185], v[214:217], v[0:3]
	s_add_i32 s65, s65, 2
	s_add_u32 s4, s4, 0x100
	s_addc_u32 s5, s5, 0
	s_add_u32 s63, s63, 0x100
	s_addc_u32 s64, s64, 0
	s_cmp_gt_u32 s65, 29
	s_setprio 0
	s_barrier
	s_cbranch_scc0 .LBB0_824
	s_and_b64 vcc, exec, s[16:17]
	s_cbranch_vccz .LBB0_827
	s_barrier

; #define PG8_STAGE(bufoff, gbase, voff) do { _Pragma("unroll") for (int _i = 0; _i < 2; ++_i) \
;         __builtin_amdgcn_global_load_lds((const unsigned*)((const char*)(gbase) + (voff)[_i]), (PG8_LAS unsigned*)(lds + (bufoff) + ldsw + _i * 8192), 16, 0, 0); } while (0)
; #define PG8_LDA(dst, b, h) do { _Pragma("unroll") for (int m = 0; m < 4; ++m) _Pragma("unroll") for (int k = 0; k < 2; ++k) dst[m][k] = *(const PG8_LAS bf16x8*)(lds + PG8_SA(b, h) + aoff + m * 2048 + k * 1024); } while (0)
; #define PG8_LDB(dst, b, h) do { _Pragma("unroll") for (int n = 0; n < 2; ++n) _Pragma("unroll") for (int k = 0; k < 2; ++k) dst[n][k] = *(const PG8_LAS bf16x8*)(lds + PG8_SB(b, h) + boff + n * 2048 + k * 1024); } while (0)
; #define PG8_MMA(ai, bj, At, Bt) do { __builtin_amdgcn_s_setprio(1); _Pragma("unroll") for (int m = 0; m < 4; ++m) _Pragma("unroll") for (int n = 0; n < 2; ++n) _Pragma("unroll") for (int k = 0; k < 2; ++k) \
;         acc[ai][bj][m][n] = __builtin_amdgcn_mfma_f32_16x16x32_bf16(Bt[n][k], At[m][k], acc[ai][bj][m][n], 0, 0, 0); __builtin_amdgcn_s_setprio(0); } while (0)
; #define PG8_WAIT_V(n) asm volatile("s_waitcnt vmcnt(" #n ")" ::: "memory")
; #define PG8_WAIT_L(n) asm volatile("s_waitcnt lgkmcnt(" #n ")" ::: "memory")
; template <class Epi, class Sched, bool ALIGN_EPI = false, bool SP2 = false>
; __device__ __forceinline__ void gemm_phase(PG8_LAS unsigned char* lds, const Gemm g, const Sched& S, const Epi& E) {
;     ...
;             const bool last = (t == nt - 2);
;             const char* a1 = cA + (size_t)(t + 1) * kstep;
;             const char* a2 = last ? nA : cA + (size_t)(t + 2) * kstep; const char* b2 = last ? nB : cB + (size_t)(t + 2) * kstep;
;             const char* a3 = a2 + kstep; const char* b3 = b2 + kstep;
;             if (last && has_next) S.a_ready(nxt);
;             if constexpr (SP2) {
;             PG8_LDB(B0, 0, 0); PG8_LDB(B1, 0, 1); PG8_SCHED; PG8_LDA(At, 0, 0); PG8_STAGE(PG8_SA(1, 1), a1 + hstepA, voffA);
;             PG8_WAIT_V(8); PG8_WAIT_L(0); PG8_BAR; PG8_MMA(0, 0, At, B0); PG8_MMA(0, 1, At, B1); PG8_BAR; PG8_SCHED;
;             PG8_LDA(At, 0, 1); PG8_STAGE(PG8_SB(0, 0), b2, voffB); PG8_STAGE(PG8_SB(0, 1), b2 + hstepB, voffB); PG8_STAGE(PG8_SA(0, 0), a2, voffA);
;             PG8_WAIT_V(8); PG8_WAIT_L(0); PG8_BAR; PG8_MMA(1, 0, At, B0); PG8_MMA(1, 1, At, B1); PG8_BAR; PG8_SCHED;
.LBB0_901:
	ds_read_b128 v[140:143], v147
	ds_read_b128 v[152:155], v147 offset:1024
	ds_read_b128 v[158:161], v147 offset:2048
	ds_read_b128 v[162:165], v147 offset:3072
	ds_read_b128 v[166:169], v148
	ds_read_b128 v[170:173], v148 offset:1024
	ds_read_b128 v[174:177], v148 offset:2048
	ds_read_b128 v[178:181], v148 offset:3072
	s_add_u32 s28, s26, 0xffe00080
	s_addc_u32 s29, s27, -1
	s_cmpk_eq_i32 s52, 0x7c
	s_cselect_b32 s31, s19, s29
	s_cselect_b32 s30, s23, s28
	s_cselect_b32 s29, s17, s51
	s_cselect_b32 s28, s49, s50
	v_lshl_add_u64 v[214:215], s[26:27], 0, v[132:133]
	s_add_i32 m0, s25, 0xc000
	ds_read_b128 v[182:185], v149
	ds_read_b128 v[186:189], v149 offset:1024
	ds_read_b128 v[190:193], v149 offset:2048
	ds_read_b128 v[194:197], v149 offset:3072
	ds_read_b128 v[198:201], v149 offset:4096
	ds_read_b128 v[202:205], v149 offset:5120
	ds_read_b128 v[206:209], v149 offset:6144
	ds_read_b128 v[210:213], v149 offset:7168
	global_load_lds_dwordx4 v[214:215], off
	v_lshl_add_u64 v[214:215], s[26:27], 0, v[134:135]
	s_add_i32 m0, s25, 0xe000
	s_nop 0
	global_load_lds_dwordx4 v[214:215], off
	s_waitcnt vmcnt(8)
	s_waitcnt lgkmcnt(0)
	s_barrier
	s_setprio 1
	s_waitcnt lgkmcnt(0)
	v_mfma_f32_16x16x32_bf16 v[124:127], v[140:143], v[182:185], v[124:127]
	v_mfma_f32_16x16x32_bf16 v[120:123], v[158:161], v[182:185], v[120:123]
	v_mfma_f32_16x16x32_bf16 v[108:111], v[140:143], v[190:193], v[108:111]
	v_mfma_f32_16x16x32_bf16 v[104:107], v[158:161], v[190:193], v[104:107]
	v_mfma_f32_16x16x32_bf16 v[92:95], v[140:143], v[198:201], v[92:95]
	v_mfma_f32_16x16x32_bf16 v[88:91], v[158:161], v[198:201], v[88:91]
	v_mfma_f32_16x16x32_bf16 v[76:79], v[140:143], v[206:209], v[76:79]
	v_mfma_f32_16x16x32_bf16 v[72:75], v[158:161], v[206:209], v[72:75]
	v_mfma_f32_16x16x32_bf16 v[124:127], v[152:155], v[186:189], v[124:127]
	v_mfma_f32_16x16x32_bf16 v[120:123], v[162:165], v[186:189], v[120:123]
	v_mfma_f32_16x16x32_bf16 v[108:111], v[152:155], v[194:197], v[108:111]
	v_mfma_f32_16x16x32_bf16 v[104:107], v[162:165], v[194:197], v[104:107]
	v_mfma_f32_16x16x32_bf16 v[92:95], v[152:155], v[202:205], v[92:95]
	v_mfma_f32_16x16x32_bf16 v[88:91], v[162:165], v[202:205], v[88:91]
	v_mfma_f32_16x16x32_bf16 v[76:79], v[152:155], v[210:213], v[76:79]
	v_mfma_f32_16x16x32_bf16 v[72:75], v[162:165], v[210:213], v[72:75]
	v_mfma_f32_16x16x32_bf16 v[116:119], v[166:169], v[182:185], v[116:119]
	v_mfma_f32_16x16x32_bf16 v[112:115], v[174:177], v[182:185], v[112:115]
	v_mfma_f32_16x16x32_bf16 v[100:103], v[166:169], v[190:193], v[100:103]
	v_mfma_f32_16x16x32_bf16 v[96:99], v[174:177], v[190:193], v[96:99]
	v_mfma_f32_16x16x32_bf16 v[84:87], v[166:169], v[198:201], v[84:87]
	v_mfma_f32_16x16x32_bf16 v[80:83], v[174:177], v[198:201], v[80:83]
	v_mfma_f32_16x16x32_bf16 v[68:71], v[166:169], v[206:209], v[68:71]
	v_mfma_f32_16x16x32_bf16 v[64:67], v[174:177], v[206:209], v[64:67]
	v_mfma_f32_16x16x32_bf16 v[116:119], v[170:173], v[186:189], v[116:119]
	v_mfma_f32_16x16x32_bf16 v[112:115], v[178:181], v[186:189], v[112:115]
	v_mfma_f32_16x16x32_bf16 v[100:103], v[170:173], v[194:197], v[100:103]
	v_mfma_f32_16x16x32_bf16 v[96:99], v[178:181], v[194:197], v[96:99]
	v_mfma_f32_16x16x32_bf16 v[84:87], v[170:173], v[202:205], v[84:87]
	v_mfma_f32_16x16x32_bf16 v[80:83], v[178:181], v[202:205], v[80:83]
	v_mfma_f32_16x16x32_bf16 v[68:71], v[170:173], v[210:213], v[68:71]
	v_mfma_f32_16x16x32_bf16 v[64:67], v[178:181], v[210:213], v[64:67]
	s_setprio 0
	s_barrier
	s_add_i32 s53, s47, s38
	v_lshl_add_u64 v[214:215], s[28:29], 0, v[128:129]
	s_mov_b32 m0, s53
	ds_read_b128 v[182:185], v149 offset:16384
	ds_read_b128 v[186:189], v149 offset:17408
	ds_read_b128 v[190:193], v149 offset:18432
	ds_read_b128 v[194:197], v149 offset:19456
	ds_read_b128 v[198:201], v149 offset:20480
	ds_read_b128 v[202:205], v149 offset:21504
	ds_read_b128 v[206:209], v149 offset:22528
	ds_read_b128 v[210:213], v149 offset:23552
	global_load_lds_dwordx4 v[214:215], off
	s_add_i32 m0, s53, 0x2000
	s_add_u32 s54, s28, 0x200000
	v_lshl_add_u64 v[216:217], s[28:29], 0, v[130:131]
	s_addc_u32 s55, s29, 0
	s_add_i32 s53, s48, s38
	global_load_lds_dwordx4 v[216:217], off
	v_lshl_add_u64 v[218:219], s[54:55], 0, v[128:129]
	s_mov_b32 m0, s53
	v_lshl_add_u64 v[220:221], s[30:31], 0, v[130:131]
	global_load_lds_dwordx4 v[218:219], off
	v_lshl_add_u64 v[218:219], s[54:55], 0, v[130:131]
	s_add_i32 m0, s53, 0x2000
	s_nop 0
	global_load_lds_dwordx4 v[218:219], off
	v_lshl_add_u64 v[218:219], s[30:31], 0, v[128:129]
	s_mov_b32 m0, s25
	s_nop 0
	global_load_lds_dwordx4 v[218:219], off
	s_mov_b32 m0, s39
	s_nop 0
	global_load_lds_dwordx4 v[220:221], off
	s_waitcnt vmcnt(8)
	s_waitcnt lgkmcnt(0)
	s_barrier
; #define PG8_STAGE(bufoff, gbase, voff) do { _Pragma("unroll") for (int _i = 0; _i < 2; ++_i) \
;         __builtin_amdgcn_global_load_lds((const unsigned*)((const char*)(gbase) + (voff)[_i]), (PG8_LAS unsigned*)(lds + (bufoff) + ldsw + _i * 8192), 16, 0, 0); } while (0)
; #define PG8_LDA(dst, b, h) do { _Pragma("unroll") for (int m = 0; m < 4; ++m) _Pragma("unroll") for (int k = 0; k < 2; ++k) dst[m][k] = *(const PG8_LAS bf16x8*)(lds + PG8_SA(b, h) + aoff + m * 2048 + k * 1024); } while (0)
; #define PG8_LDB(dst, b, h) do { _Pragma("unroll") for (int n = 0; n < 2; ++n) _Pragma("unroll") for (int k = 0; k < 2; ++k) dst[n][k] = *(const PG8_LAS bf16x8*)(lds + PG8_SB(b, h) + boff + n * 2048 + k * 1024); } while (0)
; #define PG8_MMA(ai, bj, At, Bt) do { __builtin_amdgcn_s_setprio(1); _Pragma("unroll") for (int m = 0; m < 4; ++m) _Pragma("unroll") for (int n = 0; n < 2; ++n) _Pragma("unroll") for (int k = 0; k < 2; ++k) \
;         acc[ai][bj][m][n] = __builtin_amdgcn_mfma_f32_16x16x32_bf16(Bt[n][k], At[m][k], acc[ai][bj][m][n], 0, 0, 0); __builtin_amdgcn_s_setprio(0); } while (0)
; #define PG8_WAIT_V(n) asm volatile("s_waitcnt vmcnt(" #n ")" ::: "memory")
; #define PG8_WAIT_L(n) asm volatile("s_waitcnt lgkmcnt(" #n ")" ::: "memory")
; #define PG8_BAR __builtin_amdgcn_s_barrier()
; #define PG8_SCHED __builtin_amdgcn_sched_barrier(0)
; template <class Epi, class Sched, bool ALIGN_EPI = false, bool SP2 = false>
; __device__ __forceinline__ void gemm_phase(PG8_LAS unsigned char* lds, const Gemm g, const Sched& S, const Epi& E) {
;     ...
;             PG8_WAIT_V(8); PG8_WAIT_L(0); PG8_BAR; PG8_MMA(1, 0, At, B0); PG8_MMA(1, 1, At, B1); PG8_BAR; PG8_SCHED;
;             PG8_LDB(B0, 1, 0); PG8_LDB(B1, 1, 1); PG8_SCHED; PG8_LDA(At, 1, 0); PG8_STAGE(PG8_SA(0, 1), a2 + hstepA, voffA);
;             PG8_WAIT_V(8); PG8_WAIT_L(0); PG8_BAR; PG8_MMA(0, 0, At, B0); PG8_MMA(0, 1, At, B1); PG8_BAR; PG8_SCHED;
	s_setprio 1
	s_waitcnt lgkmcnt(0)
	v_mfma_f32_16x16x32_bf16 v[60:63], v[140:143], v[182:185], v[60:63]
	v_mfma_f32_16x16x32_bf16 v[56:59], v[158:161], v[182:185], v[56:59]
	v_mfma_f32_16x16x32_bf16 v[44:47], v[140:143], v[190:193], v[44:47]
	v_mfma_f32_16x16x32_bf16 v[40:43], v[158:161], v[190:193], v[40:43]
	v_mfma_f32_16x16x32_bf16 v[28:31], v[140:143], v[198:201], v[28:31]
	v_mfma_f32_16x16x32_bf16 v[24:27], v[158:161], v[198:201], v[24:27]
	v_mfma_f32_16x16x32_bf16 v[12:15], v[140:143], v[206:209], v[12:15]
	v_mfma_f32_16x16x32_bf16 v[8:11], v[158:161], v[206:209], v[8:11]
	v_mfma_f32_16x16x32_bf16 v[60:63], v[152:155], v[186:189], v[60:63]
	v_mfma_f32_16x16x32_bf16 v[56:59], v[162:165], v[186:189], v[56:59]
	v_mfma_f32_16x16x32_bf16 v[44:47], v[152:155], v[194:197], v[44:47]
	v_mfma_f32_16x16x32_bf16 v[40:43], v[162:165], v[194:197], v[40:43]
	v_mfma_f32_16x16x32_bf16 v[28:31], v[152:155], v[202:205], v[28:31]
	v_mfma_f32_16x16x32_bf16 v[24:27], v[162:165], v[202:205], v[24:27]
	v_mfma_f32_16x16x32_bf16 v[12:15], v[152:155], v[210:213], v[12:15]
	v_mfma_f32_16x16x32_bf16 v[8:11], v[162:165], v[210:213], v[8:11]
	v_mfma_f32_16x16x32_bf16 v[52:55], v[166:169], v[182:185], v[52:55]
	v_mfma_f32_16x16x32_bf16 v[48:51], v[174:177], v[182:185], v[48:51]
	v_mfma_f32_16x16x32_bf16 v[36:39], v[166:169], v[190:193], v[36:39]
	v_mfma_f32_16x16x32_bf16 v[32:35], v[174:177], v[190:193], v[32:35]
	v_mfma_f32_16x16x32_bf16 v[20:23], v[166:169], v[198:201], v[20:23]
	v_mfma_f32_16x16x32_bf16 v[16:19], v[174:177], v[198:201], v[16:19]
	v_mfma_f32_16x16x32_bf16 v[4:7], v[166:169], v[206:209], v[4:7]
	v_mfma_f32_16x16x32_bf16 v[0:3], v[174:177], v[206:209], v[0:3]
	v_mfma_f32_16x16x32_bf16 v[52:55], v[170:173], v[186:189], v[52:55]
	v_mfma_f32_16x16x32_bf16 v[48:51], v[178:181], v[186:189], v[48:51]
	v_mfma_f32_16x16x32_bf16 v[36:39], v[170:173], v[194:197], v[36:39]
	v_mfma_f32_16x16x32_bf16 v[32:35], v[178:181], v[194:197], v[32:35]
	v_mfma_f32_16x16x32_bf16 v[20:23], v[170:173], v[202:205], v[20:23]
	v_mfma_f32_16x16x32_bf16 v[16:19], v[178:181], v[202:205], v[16:19]
	v_mfma_f32_16x16x32_bf16 v[4:7], v[170:173], v[210:213], v[4:7]
	v_mfma_f32_16x16x32_bf16 v[0:3], v[178:181], v[210:213], v[0:3]
	s_setprio 0
	s_barrier
	s_add_i32 s53, 0, 0x18000
	v_add_u32_e32 v151, s53, v145
	s_add_i32 s54, 0, 0x1c000
	ds_read_b128 v[140:143], v151
	ds_read_b128 v[152:155], v151 offset:1024
	ds_read_b128 v[158:161], v151 offset:2048
	ds_read_b128 v[162:165], v151 offset:3072
	v_add_u32_e32 v151, s54, v145
	ds_read_b128 v[166:169], v151
	ds_read_b128 v[170:173], v151 offset:1024
	ds_read_b128 v[174:177], v151 offset:2048
	ds_read_b128 v[178:181], v151 offset:3072
	s_add_u32 s30, s30, 0x200000
	s_addc_u32 s31, s31, 0
	s_mov_b32 m0, s40
	v_lshl_add_u64 v[222:223], s[30:31], 0, v[128:129]
	ds_read_b128 v[182:185], v149 offset:32768
	ds_read_b128 v[186:189], v149 offset:33792
	ds_read_b128 v[190:193], v149 offset:34816
	ds_read_b128 v[194:197], v149 offset:35840
	ds_read_b128 v[198:201], v149 offset:36864
	ds_read_b128 v[202:205], v149 offset:37888
	ds_read_b128 v[206:209], v149 offset:38912
	ds_read_b128 v[210:213], v149 offset:39936
	global_load_lds_dwordx4 v[222:223], off
	v_lshl_add_u64 v[222:223], s[30:31], 0, v[130:131]
	s_mov_b32 m0, s41
	s_nop 0
	global_load_lds_dwordx4 v[222:223], off
	s_waitcnt vmcnt(8)
	s_waitcnt lgkmcnt(0)
	s_barrier
	s_setprio 1
	s_waitcnt lgkmcnt(0)
	v_mfma_f32_16x16x32_bf16 v[124:127], v[140:143], v[182:185], v[124:127]
	v_mfma_f32_16x16x32_bf16 v[120:123], v[158:161], v[182:185], v[120:123]
	v_mfma_f32_16x16x32_bf16 v[108:111], v[140:143], v[190:193], v[108:111]
	v_mfma_f32_16x16x32_bf16 v[104:107], v[158:161], v[190:193], v[104:107]
	v_mfma_f32_16x16x32_bf16 v[92:95], v[140:143], v[198:201], v[92:95]
	v_mfma_f32_16x16x32_bf16 v[88:91], v[158:161], v[198:201], v[88:91]
	v_mfma_f32_16x16x32_bf16 v[76:79], v[140:143], v[206:209], v[76:79]
	v_mfma_f32_16x16x32_bf16 v[72:75], v[158:161], v[206:209], v[72:75]
	v_mfma_f32_16x16x32_bf16 v[124:127], v[152:155], v[186:189], v[124:127]
	v_mfma_f32_16x16x32_bf16 v[120:123], v[162:165], v[186:189], v[120:123]
	v_mfma_f32_16x16x32_bf16 v[108:111], v[152:155], v[194:197], v[108:111]
	v_mfma_f32_16x16x32_bf16 v[104:107], v[162:165], v[194:197], v[104:107]
	v_mfma_f32_16x16x32_bf16 v[92:95], v[152:155], v[202:205], v[92:95]
	v_mfma_f32_16x16x32_bf16 v[88:91], v[162:165], v[202:205], v[88:91]
	v_mfma_f32_16x16x32_bf16 v[76:79], v[152:155], v[210:213], v[76:79]
	v_mfma_f32_16x16x32_bf16 v[72:75], v[162:165], v[210:213], v[72:75]
	v_mfma_f32_16x16x32_bf16 v[116:119], v[166:169], v[182:185], v[116:119]
	v_mfma_f32_16x16x32_bf16 v[112:115], v[174:177], v[182:185], v[112:115]
	v_mfma_f32_16x16x32_bf16 v[100:103], v[166:169], v[190:193], v[100:103]
	v_mfma_f32_16x16x32_bf16 v[96:99], v[174:177], v[190:193], v[96:99]
	v_mfma_f32_16x16x32_bf16 v[84:87], v[166:169], v[198:201], v[84:87]
	v_mfma_f32_16x16x32_bf16 v[80:83], v[174:177], v[198:201], v[80:83]
	v_mfma_f32_16x16x32_bf16 v[68:71], v[166:169], v[206:209], v[68:71]
	v_mfma_f32_16x16x32_bf16 v[64:67], v[174:177], v[206:209], v[64:67]
	v_mfma_f32_16x16x32_bf16 v[116:119], v[170:173], v[186:189], v[116:119]
	v_mfma_f32_16x16x32_bf16 v[112:115], v[178:181], v[186:189], v[112:115]
	v_mfma_f32_16x16x32_bf16 v[100:103], v[170:173], v[194:197], v[100:103]
	v_mfma_f32_16x16x32_bf16 v[96:99], v[178:181], v[194:197], v[96:99]
	v_mfma_f32_16x16x32_bf16 v[84:87], v[170:173], v[202:205], v[84:87]
	v_mfma_f32_16x16x32_bf16 v[80:83], v[178:181], v[202:205], v[80:83]
	v_mfma_f32_16x16x32_bf16 v[68:71], v[170:173], v[210:213], v[68:71]
	v_mfma_f32_16x16x32_bf16 v[64:67], v[178:181], v[210:213], v[64:67]
	s_setprio 0
	s_barrier
; #define PG8_STAGE(bufoff, gbase, voff) do { _Pragma("unroll") for (int _i = 0; _i < 2; ++_i) \
;         __builtin_amdgcn_global_load_lds((const unsigned*)((const char*)(gbase) + (voff)[_i]), (PG8_LAS unsigned*)(lds + (bufoff) + ldsw + _i * 8192), 16, 0, 0); } while (0)
; #define PG8_LDA(dst, b, h) do { _Pragma("unroll") for (int m = 0; m < 4; ++m) _Pragma("unroll") for (int k = 0; k < 2; ++k) dst[m][k] = *(const PG8_LAS bf16x8*)(lds + PG8_SA(b, h) + aoff + m * 2048 + k * 1024); } while (0)
; #define PG8_MMA(ai, bj, At, Bt) do { __builtin_amdgcn_s_setprio(1); _Pragma("unroll") for (int m = 0; m < 4; ++m) _Pragma("unroll") for (int n = 0; n < 2; ++n) _Pragma("unroll") for (int k = 0; k < 2; ++k) \
;         acc[ai][bj][m][n] = __builtin_amdgcn_mfma_f32_16x16x32_bf16(Bt[n][k], At[m][k], acc[ai][bj][m][n], 0, 0, 0); __builtin_amdgcn_s_setprio(0); } while (0)
; #define PG8_WAIT_V(n) asm volatile("s_waitcnt vmcnt(" #n ")" ::: "memory")
; #define PG8_WAIT_L(n) asm volatile("s_waitcnt lgkmcnt(" #n ")" ::: "memory")
; #define PG8_BAR __builtin_amdgcn_s_barrier()
; #define PG8_SCHED __builtin_amdgcn_sched_barrier(0)
; template <class Epi, class Sched, bool ALIGN_EPI = false, bool SP2 = false>
; __device__ __forceinline__ void gemm_phase(PG8_LAS unsigned char* lds, const Gemm g, const Sched& S, const Epi& E) {
;     ...
;         for (int t = 0; t < nt; t += 2) {
;     ...
;             PG8_LDA(At, 1, 1); PG8_STAGE(PG8_SB(1, 0), b3, voffB); PG8_STAGE(PG8_SB(1, 1), b3 + hstepB, voffB); PG8_STAGE(PG8_SA(1, 0), a3, voffA);
;             PG8_WAIT_V(8); PG8_WAIT_L(0); PG8_BAR; PG8_MMA(1, 0, At, B0); PG8_MMA(1, 1, At, B1); PG8_BAR; PG8_SCHED;
	s_add_i32 s30, s53, s38
	v_lshl_add_u64 v[214:215], v[214:215], 0, s[12:13]
	s_mov_b32 m0, s30
	ds_read_b128 v[182:185], v149 offset:49152
	ds_read_b128 v[186:189], v149 offset:50176
	ds_read_b128 v[190:193], v149 offset:51200
	ds_read_b128 v[194:197], v149 offset:52224
	ds_read_b128 v[198:201], v149 offset:53248
	ds_read_b128 v[202:205], v149 offset:54272
	ds_read_b128 v[206:209], v149 offset:55296
	ds_read_b128 v[210:213], v149 offset:56320
	global_load_lds_dwordx4 v[214:215], off
	s_add_i32 m0, s30, 0x2000
	s_add_u32 s28, s28, 0x200080
	v_lshl_add_u64 v[214:215], v[216:217], 0, s[12:13]
	s_addc_u32 s29, s29, 0
	s_add_i32 s30, s54, s38
	global_load_lds_dwordx4 v[214:215], off
	v_lshl_add_u64 v[214:215], s[28:29], 0, v[128:129]
	s_mov_b32 m0, s30
	s_nop 0
	global_load_lds_dwordx4 v[214:215], off
	v_lshl_add_u64 v[214:215], s[28:29], 0, v[130:131]
	s_add_i32 m0, s30, 0x2000
	s_nop 0
	global_load_lds_dwordx4 v[214:215], off
	v_lshl_add_u64 v[214:215], v[218:219], 0, s[12:13]
	s_mov_b32 m0, s43
	s_nop 0
	global_load_lds_dwordx4 v[214:215], off
	v_lshl_add_u64 v[214:215], v[220:221], 0, s[12:13]
	s_mov_b32 m0, s44
	s_nop 0
	global_load_lds_dwordx4 v[214:215], off
	s_waitcnt vmcnt(8)
	s_waitcnt lgkmcnt(0)
	s_barrier
	s_setprio 1
	s_waitcnt lgkmcnt(0)
	v_mfma_f32_16x16x32_bf16 v[60:63], v[140:143], v[182:185], v[60:63]
	v_mfma_f32_16x16x32_bf16 v[56:59], v[158:161], v[182:185], v[56:59]
	v_mfma_f32_16x16x32_bf16 v[44:47], v[140:143], v[190:193], v[44:47]
	v_mfma_f32_16x16x32_bf16 v[40:43], v[158:161], v[190:193], v[40:43]
	v_mfma_f32_16x16x32_bf16 v[28:31], v[140:143], v[198:201], v[28:31]
	v_mfma_f32_16x16x32_bf16 v[24:27], v[158:161], v[198:201], v[24:27]
	v_mfma_f32_16x16x32_bf16 v[12:15], v[140:143], v[206:209], v[12:15]
	v_mfma_f32_16x16x32_bf16 v[8:11], v[158:161], v[206:209], v[8:11]
	v_mfma_f32_16x16x32_bf16 v[60:63], v[152:155], v[186:189], v[60:63]
	v_mfma_f32_16x16x32_bf16 v[56:59], v[162:165], v[186:189], v[56:59]
	v_mfma_f32_16x16x32_bf16 v[44:47], v[152:155], v[194:197], v[44:47]
	v_mfma_f32_16x16x32_bf16 v[40:43], v[162:165], v[194:197], v[40:43]
	v_mfma_f32_16x16x32_bf16 v[28:31], v[152:155], v[202:205], v[28:31]
	v_mfma_f32_16x16x32_bf16 v[24:27], v[162:165], v[202:205], v[24:27]
	v_mfma_f32_16x16x32_bf16 v[12:15], v[152:155], v[210:213], v[12:15]
	v_mfma_f32_16x16x32_bf16 v[8:11], v[162:165], v[210:213], v[8:11]
	v_mfma_f32_16x16x32_bf16 v[52:55], v[166:169], v[182:185], v[52:55]
	v_mfma_f32_16x16x32_bf16 v[48:51], v[174:177], v[182:185], v[48:51]
	v_mfma_f32_16x16x32_bf16 v[36:39], v[166:169], v[190:193], v[36:39]
	v_mfma_f32_16x16x32_bf16 v[32:35], v[174:177], v[190:193], v[32:35]
	v_mfma_f32_16x16x32_bf16 v[20:23], v[166:169], v[198:201], v[20:23]
	v_mfma_f32_16x16x32_bf16 v[16:19], v[174:177], v[198:201], v[16:19]
	v_mfma_f32_16x16x32_bf16 v[4:7], v[166:169], v[206:209], v[4:7]
	v_mfma_f32_16x16x32_bf16 v[0:3], v[174:177], v[206:209], v[0:3]
	v_mfma_f32_16x16x32_bf16 v[52:55], v[170:173], v[186:189], v[52:55]
	v_mfma_f32_16x16x32_bf16 v[48:51], v[178:181], v[186:189], v[48:51]
	v_mfma_f32_16x16x32_bf16 v[36:39], v[170:173], v[194:197], v[36:39]
	v_mfma_f32_16x16x32_bf16 v[32:35], v[178:181], v[194:197], v[32:35]
	v_mfma_f32_16x16x32_bf16 v[20:23], v[170:173], v[202:205], v[20:23]
	v_mfma_f32_16x16x32_bf16 v[16:19], v[178:181], v[202:205], v[16:19]
	v_mfma_f32_16x16x32_bf16 v[4:7], v[170:173], v[210:213], v[4:7]
	v_mfma_f32_16x16x32_bf16 v[0:3], v[178:181], v[210:213], v[0:3]
	s_add_i32 s52, s52, 2
	s_add_u32 s26, s26, 0x100
	s_addc_u32 s27, s27, 0
	s_add_u32 s50, s50, 0x100
	s_addc_u32 s51, s51, 0
	s_cmpk_gt_u32 s52, 0x7d
	s_setprio 0
	s_barrier
	s_cbranch_scc0 .LBB0_901
	s_and_b64 vcc, exec, s[14:15]
	s_cbranch_vccz .LBB0_904
	s_barrier
